# 8 instead of 4 MFMAs ahead of the segment barrier, on the full-segment snake chain order
# baseline (speedup 1.0000x reference)
; #define PG8_STAGE(bufoff, gbase, voff) do { _Pragma("unroll") for (int _i = 0; _i < 2; ++_i) \
;         __builtin_amdgcn_global_load_lds((const unsigned*)((const char*)(gbase) + (voff)[_i]), (PG8_LAS unsigned*)(lds + (bufoff) + ldsw + _i * 8192), 16, 0, 0); } while (0)
; #define PG8_LDA(dst, b, h) do { _Pragma("unroll") for (int m = 0; m < 4; ++m) _Pragma("unroll") for (int k = 0; k < 2; ++k) dst[m][k] = *(const PG8_LAS bf16x8*)(lds + PG8_SA(b, h) + aoff + m * 2048 + k * 1024); } while (0)
; #define PG8_LDB(dst, b, h) do { _Pragma("unroll") for (int n = 0; n < 2; ++n) _Pragma("unroll") for (int k = 0; k < 2; ++k) dst[n][k] = *(const PG8_LAS bf16x8*)(lds + PG8_SB(b, h) + boff + n * 2048 + k * 1024); } while (0)
; #define PG8_MMA(ai, bj, At, Bt) do { __builtin_amdgcn_s_setprio(1); _Pragma("unroll") for (int m = 0; m < 4; ++m) _Pragma("unroll") for (int n = 0; n < 2; ++n) _Pragma("unroll") for (int k = 0; k < 2; ++k) \
;         acc[ai][bj][m][n] = __builtin_amdgcn_mfma_f32_16x16x32_bf16(Bt[n][k], At[m][k], acc[ai][bj][m][n], 0, 0, 0); __builtin_amdgcn_s_setprio(0); } while (0)
; #define PG8_WAIT_V(n) asm volatile("s_waitcnt vmcnt(" #n ")" ::: "memory")
; #define PG8_BAR __builtin_amdgcn_s_barrier()
; template <class Epi, class Sched, bool ALIGN_EPI = false, bool SP2 = false, bool ABLK = false, bool BBLK = false>
; __device__ __forceinline__ void gemm_phase(PG8_LAS unsigned char* lds, const Gemm g, const Sched& S, const Epi& E) {
;     ...
;             const bool last = (t == nt - 2);
;             const char* a1 = cA + (size_t)(t + 1) * kstepA;
;             const char* a2 = last ? nA : cA + (size_t)(t + 2) * kstepA; const char* b2 = last ? nB : cB + (size_t)(t + 2) * kstepB;
;             const char* a3 = a2 + kstepA; const char* b3 = b2 + kstepB;
;             if (last && has_next) S.a_ready(nxt);
;             if constexpr (SP2) {
;             PG8_LDB(B0, 0, 0); PG8_LDB(B1, 0, 1); PG8_SCHED; PG8_LDA(At, 0, 0); PG8_STAGE(PG8_SA(1, 1), a1 + hstepA, voffA);
;             PG8_WAIT_V(8); PG8_WAIT_L(0); PG8_BAR; PG8_MMA(0, 0, At, B0); PG8_MMA(0, 1, At, B1); PG8_BAR; PG8_SCHED;
;             PG8_LDA(At, 0, 1); PG8_STAGE(PG8_SB(0, 0), b2, voffB); PG8_STAGE(PG8_SB(0, 1), b2 + hstepB, voffB); PG8_STAGE(PG8_SA(0, 0), a2, voffA);
;             PG8_WAIT_V(8); PG8_WAIT_L(0); PG8_BAR; PG8_MMA(1, 0, At, B0); PG8_MMA(1, 1, At, B1); PG8_BAR; PG8_SCHED;
.LBB0_185:
	s_add_u32 s13, s20, 0x4000
	s_addc_u32 s22, s21, 0
	s_cmp_eq_u32 vcc_hi, 28
	s_cselect_b32 s26, s70, s13
	s_cselect_b32 s27, s9, s22
	s_cselect_b32 s24, s71, s77
	s_cselect_b32 s25, s7, vcc_lo
	s_add_u32 s22, s26, 0x8000
	s_addc_u32 s23, s27, 0
	s_add_i32 s13, 0, 0x10000
	v_add_u32_e32 v36, s13, v160
	s_add_i32 s88, 0, 0x14000
	ds_read_b128 v[152:155], v36
	ds_read_b128 v[156:159], v36 offset:1024
	ds_read_b128 v[162:165], v36 offset:2048
	ds_read_b128 v[166:169], v36 offset:3072
	v_add_u32_e32 v36, s88, v160
	ds_read_b128 v[170:173], v36
	ds_read_b128 v[174:177], v36 offset:1024
	ds_read_b128 v[178:181], v36 offset:2048
	ds_read_b128 v[182:185], v36 offset:3072
	s_add_i32 m0, s19, 0xc000
	ds_read_b128 v[186:189], v161
	ds_read_b128 v[190:193], v161 offset:1024
	ds_read_b128 v[194:197], v161 offset:2048
	ds_read_b128 v[198:201], v161 offset:3072
	ds_read_b128 v[202:205], v161 offset:4096
	ds_read_b128 v[206:209], v161 offset:5120
	ds_read_b128 v[210:213], v161 offset:6144
	ds_read_b128 v[214:217], v161 offset:7168
	global_load_lds_dwordx4 v148, s[20:21]
	s_add_i32 m0, s19, 0xe000
	s_nop 0
	global_load_lds_dwordx4 v150, s[20:21]
	s_waitcnt vmcnt(8)
	s_waitcnt lgkmcnt(0)
	v_mfma_f32_16x16x32_bf16 v[132:135], v[152:155], v[186:189], v[132:135]
	v_mfma_f32_16x16x32_bf16 v[132:135], v[156:159], v[190:193], v[132:135]
	v_mfma_f32_16x16x32_bf16 v[128:131], v[166:169], v[190:193], v[128:131]
	v_mfma_f32_16x16x32_bf16 v[128:131], v[162:165], v[186:189], v[128:131]
	v_mfma_f32_16x16x32_bf16 v[112:115], v[162:165], v[194:197], v[112:115]
	v_mfma_f32_16x16x32_bf16 v[112:115], v[166:169], v[198:201], v[112:115]
	v_mfma_f32_16x16x32_bf16 v[116:119], v[156:159], v[198:201], v[116:119]
	v_mfma_f32_16x16x32_bf16 v[116:119], v[152:155], v[194:197], v[116:119]
	s_barrier
	s_setprio 1
	v_mfma_f32_16x16x32_bf16 v[100:103], v[152:155], v[202:205], v[100:103]
	v_mfma_f32_16x16x32_bf16 v[100:103], v[156:159], v[206:209], v[100:103]
	v_mfma_f32_16x16x32_bf16 v[96:99], v[166:169], v[206:209], v[96:99]
	v_mfma_f32_16x16x32_bf16 v[96:99], v[162:165], v[202:205], v[96:99]
	v_mfma_f32_16x16x32_bf16 v[80:83], v[162:165], v[210:213], v[80:83]
	v_mfma_f32_16x16x32_bf16 v[80:83], v[166:169], v[214:217], v[80:83]
	v_mfma_f32_16x16x32_bf16 v[84:87], v[156:159], v[214:217], v[84:87]
	v_mfma_f32_16x16x32_bf16 v[84:87], v[152:155], v[210:213], v[84:87]
	s_setprio 0
	s_setprio 1
	v_mfma_f32_16x16x32_bf16 v[76:79], v[170:173], v[210:213], v[76:79]
	v_mfma_f32_16x16x32_bf16 v[76:79], v[174:177], v[214:217], v[76:79]
	v_mfma_f32_16x16x32_bf16 v[124:127], v[174:177], v[190:193], v[124:127]
	v_mfma_f32_16x16x32_bf16 v[124:127], v[170:173], v[186:189], v[124:127]
	v_mfma_f32_16x16x32_bf16 v[120:123], v[178:181], v[186:189], v[120:123]
	v_mfma_f32_16x16x32_bf16 v[120:123], v[182:185], v[190:193], v[120:123]
	v_mfma_f32_16x16x32_bf16 v[104:107], v[182:185], v[198:201], v[104:107]
	v_mfma_f32_16x16x32_bf16 v[104:107], v[178:181], v[194:197], v[104:107]
	v_mfma_f32_16x16x32_bf16 v[108:111], v[170:173], v[194:197], v[108:111]
	v_mfma_f32_16x16x32_bf16 v[108:111], v[174:177], v[198:201], v[108:111]
	v_mfma_f32_16x16x32_bf16 v[92:95], v[174:177], v[206:209], v[92:95]
	v_mfma_f32_16x16x32_bf16 v[92:95], v[170:173], v[202:205], v[92:95]
	v_mfma_f32_16x16x32_bf16 v[88:91], v[178:181], v[202:205], v[88:91]
	v_mfma_f32_16x16x32_bf16 v[88:91], v[182:185], v[206:209], v[88:91]
	v_mfma_f32_16x16x32_bf16 v[72:75], v[182:185], v[214:217], v[72:75]
	v_mfma_f32_16x16x32_bf16 v[72:75], v[178:181], v[210:213], v[72:75]
	s_setprio 0
	s_barrier
	s_add_i32 s13, s13, s31
	s_mov_b32 m0, s13
	ds_read_b128 v[186:189], v161 offset:16384
	ds_read_b128 v[190:193], v161 offset:17408
	ds_read_b128 v[194:197], v161 offset:18432
	ds_read_b128 v[198:201], v161 offset:19456
	ds_read_b128 v[202:205], v161 offset:20480
	ds_read_b128 v[206:209], v161 offset:21504
	ds_read_b128 v[210:213], v161 offset:22528
	ds_read_b128 v[214:217], v161 offset:23552
	global_load_lds_dwordx4 v140, s[24:25]
	s_add_i32 m0, s13, 0x2000
	s_add_u32 s68, s24, 0x4000
	s_addc_u32 s69, s25, 0
	s_add_i32 s13, s88, s31
	global_load_lds_dwordx4 v136, s[24:25]
	s_mov_b32 m0, s13
	s_nop 0
	global_load_lds_dwordx4 v140, s[68:69]
	s_add_i32 m0, s13, 0x2000
	s_nop 0
	global_load_lds_dwordx4 v136, s[68:69]
	s_mov_b32 m0, s19
	s_nop 0
	global_load_lds_dwordx4 v142, s[26:27]
	s_mov_b32 m0, s35
	s_nop 0
	global_load_lds_dwordx4 v138, s[26:27]
	s_waitcnt vmcnt(8)
	s_waitcnt lgkmcnt(0)
	v_mfma_f32_16x16x32_bf16 v[68:71], v[152:155], v[186:189], v[68:71]
	v_mfma_f32_16x16x32_bf16 v[68:71], v[156:159], v[190:193], v[68:71]
	v_mfma_f32_16x16x32_bf16 v[64:67], v[166:169], v[190:193], v[64:67]
	v_mfma_f32_16x16x32_bf16 v[64:67], v[162:165], v[186:189], v[64:67]
	v_mfma_f32_16x16x32_bf16 v[48:51], v[162:165], v[194:197], v[48:51]
	v_mfma_f32_16x16x32_bf16 v[48:51], v[166:169], v[198:201], v[48:51]
	v_mfma_f32_16x16x32_bf16 v[52:55], v[156:159], v[198:201], v[52:55]
	v_mfma_f32_16x16x32_bf16 v[52:55], v[152:155], v[194:197], v[52:55]
	s_barrier
; #define PG8_STAGE(bufoff, gbase, voff) do { _Pragma("unroll") for (int _i = 0; _i < 2; ++_i) \
;         __builtin_amdgcn_global_load_lds((const unsigned*)((const char*)(gbase) + (voff)[_i]), (PG8_LAS unsigned*)(lds + (bufoff) + ldsw + _i * 8192), 16, 0, 0); } while (0)
; #define PG8_LDA(dst, b, h) do { _Pragma("unroll") for (int m = 0; m < 4; ++m) _Pragma("unroll") for (int k = 0; k < 2; ++k) dst[m][k] = *(const PG8_LAS bf16x8*)(lds + PG8_SA(b, h) + aoff + m * 2048 + k * 1024); } while (0)
; #define PG8_LDB(dst, b, h) do { _Pragma("unroll") for (int n = 0; n < 2; ++n) _Pragma("unroll") for (int k = 0; k < 2; ++k) dst[n][k] = *(const PG8_LAS bf16x8*)(lds + PG8_SB(b, h) + boff + n * 2048 + k * 1024); } while (0)
; #define PG8_MMA(ai, bj, At, Bt) do { __builtin_amdgcn_s_setprio(1); _Pragma("unroll") for (int m = 0; m < 4; ++m) _Pragma("unroll") for (int n = 0; n < 2; ++n) _Pragma("unroll") for (int k = 0; k < 2; ++k) \
;         acc[ai][bj][m][n] = __builtin_amdgcn_mfma_f32_16x16x32_bf16(Bt[n][k], At[m][k], acc[ai][bj][m][n], 0, 0, 0); __builtin_amdgcn_s_setprio(0); } while (0)
; #define PG8_WAIT_V(n) asm volatile("s_waitcnt vmcnt(" #n ")" ::: "memory")
; #define PG8_WAIT_L(n) asm volatile("s_waitcnt lgkmcnt(" #n ")" ::: "memory")
; #define PG8_BAR __builtin_amdgcn_s_barrier()
; #define PG8_SCHED __builtin_amdgcn_sched_barrier(0)
; template <class Epi, class Sched, bool ALIGN_EPI = false, bool SP2 = false, bool ABLK = false, bool BBLK = false>
; __device__ __forceinline__ void gemm_phase(PG8_LAS unsigned char* lds, const Gemm g, const Sched& S, const Epi& E) {
;     ...
;             PG8_WAIT_V(8); PG8_WAIT_L(0); PG8_BAR; PG8_MMA(1, 0, At, B0); PG8_MMA(1, 1, At, B1); PG8_BAR; PG8_SCHED;
;             PG8_LDB(B0, 1, 0); PG8_LDB(B1, 1, 1); PG8_SCHED; PG8_LDA(At, 1, 0); PG8_STAGE(PG8_SA(0, 1), a2 + hstepA, voffA);
;             PG8_WAIT_V(8); PG8_WAIT_L(0); PG8_BAR; PG8_MMA(0, 0, At, B0); PG8_MMA(0, 1, At, B1); PG8_BAR; PG8_SCHED;
	s_setprio 1
	v_mfma_f32_16x16x32_bf16 v[32:35], v[152:155], v[202:205], v[32:35]
	v_mfma_f32_16x16x32_bf16 v[32:35], v[156:159], v[206:209], v[32:35]
	v_mfma_f32_16x16x32_bf16 v[28:31], v[166:169], v[206:209], v[28:31]
	v_mfma_f32_16x16x32_bf16 v[28:31], v[162:165], v[202:205], v[28:31]
	v_mfma_f32_16x16x32_bf16 v[12:15], v[162:165], v[210:213], v[12:15]
	v_mfma_f32_16x16x32_bf16 v[12:15], v[166:169], v[214:217], v[12:15]
	v_mfma_f32_16x16x32_bf16 v[16:19], v[156:159], v[214:217], v[16:19]
	v_mfma_f32_16x16x32_bf16 v[16:19], v[152:155], v[210:213], v[16:19]
	s_setprio 0
	s_setprio 1
	v_mfma_f32_16x16x32_bf16 v[8:11], v[170:173], v[210:213], v[8:11]
	v_mfma_f32_16x16x32_bf16 v[8:11], v[174:177], v[214:217], v[8:11]
	v_mfma_f32_16x16x32_bf16 v[60:63], v[174:177], v[190:193], v[60:63]
	v_mfma_f32_16x16x32_bf16 v[60:63], v[170:173], v[186:189], v[60:63]
	v_mfma_f32_16x16x32_bf16 v[56:59], v[178:181], v[186:189], v[56:59]
	v_mfma_f32_16x16x32_bf16 v[56:59], v[182:185], v[190:193], v[56:59]
	v_mfma_f32_16x16x32_bf16 v[40:43], v[182:185], v[198:201], v[40:43]
	v_mfma_f32_16x16x32_bf16 v[40:43], v[178:181], v[194:197], v[40:43]
	v_mfma_f32_16x16x32_bf16 v[44:47], v[170:173], v[194:197], v[44:47]
	v_mfma_f32_16x16x32_bf16 v[44:47], v[174:177], v[198:201], v[44:47]
	v_mfma_f32_16x16x32_bf16 v[24:27], v[174:177], v[206:209], v[24:27]
	v_mfma_f32_16x16x32_bf16 v[24:27], v[170:173], v[202:205], v[24:27]
	v_mfma_f32_16x16x32_bf16 v[20:23], v[178:181], v[202:205], v[20:23]
	v_mfma_f32_16x16x32_bf16 v[20:23], v[182:185], v[206:209], v[20:23]
	v_mfma_f32_16x16x32_bf16 v[4:7], v[182:185], v[214:217], v[4:7]
	v_mfma_f32_16x16x32_bf16 v[4:7], v[178:181], v[210:213], v[4:7]
	s_setprio 0
	s_barrier
	s_add_i32 s13, 0, 0x18000
	v_add_u32_e32 v36, s13, v160
	s_add_i32 s68, 0, 0x1c000
	ds_read_b128 v[152:155], v36
	ds_read_b128 v[156:159], v36 offset:1024
	ds_read_b128 v[162:165], v36 offset:2048
	ds_read_b128 v[166:169], v36 offset:3072
	v_add_u32_e32 v36, s68, v160
	ds_read_b128 v[170:173], v36
	ds_read_b128 v[174:177], v36 offset:1024
	ds_read_b128 v[178:181], v36 offset:2048
	ds_read_b128 v[182:185], v36 offset:3072
	s_add_u32 s26, s26, 0x4000
	s_addc_u32 s27, s27, 0
	s_mov_b32 m0, s36
	ds_read_b128 v[186:189], v161 offset:32768
	ds_read_b128 v[190:193], v161 offset:33792
	ds_read_b128 v[194:197], v161 offset:34816
	ds_read_b128 v[198:201], v161 offset:35840
	ds_read_b128 v[202:205], v161 offset:36864
	ds_read_b128 v[206:209], v161 offset:37888
	ds_read_b128 v[210:213], v161 offset:38912
	ds_read_b128 v[214:217], v161 offset:39936
	global_load_lds_dwordx4 v142, s[26:27]
	s_mov_b32 m0, s37
	s_nop 0
	global_load_lds_dwordx4 v138, s[26:27]
	s_waitcnt vmcnt(8)
	s_waitcnt lgkmcnt(0)
	v_mfma_f32_16x16x32_bf16 v[132:135], v[152:155], v[186:189], v[132:135]
	v_mfma_f32_16x16x32_bf16 v[132:135], v[156:159], v[190:193], v[132:135]
	v_mfma_f32_16x16x32_bf16 v[128:131], v[166:169], v[190:193], v[128:131]
	v_mfma_f32_16x16x32_bf16 v[128:131], v[162:165], v[186:189], v[128:131]
	v_mfma_f32_16x16x32_bf16 v[112:115], v[162:165], v[194:197], v[112:115]
	v_mfma_f32_16x16x32_bf16 v[112:115], v[166:169], v[198:201], v[112:115]
	v_mfma_f32_16x16x32_bf16 v[116:119], v[156:159], v[198:201], v[116:119]
	v_mfma_f32_16x16x32_bf16 v[116:119], v[152:155], v[194:197], v[116:119]
	s_barrier
	s_setprio 1
	v_mfma_f32_16x16x32_bf16 v[100:103], v[152:155], v[202:205], v[100:103]
	v_mfma_f32_16x16x32_bf16 v[100:103], v[156:159], v[206:209], v[100:103]
	v_mfma_f32_16x16x32_bf16 v[96:99], v[166:169], v[206:209], v[96:99]
	v_mfma_f32_16x16x32_bf16 v[96:99], v[162:165], v[202:205], v[96:99]
	v_mfma_f32_16x16x32_bf16 v[80:83], v[162:165], v[210:213], v[80:83]
	v_mfma_f32_16x16x32_bf16 v[80:83], v[166:169], v[214:217], v[80:83]
	v_mfma_f32_16x16x32_bf16 v[84:87], v[156:159], v[214:217], v[84:87]
	v_mfma_f32_16x16x32_bf16 v[84:87], v[152:155], v[210:213], v[84:87]
	s_setprio 0
	s_setprio 1
	v_mfma_f32_16x16x32_bf16 v[76:79], v[170:173], v[210:213], v[76:79]
	v_mfma_f32_16x16x32_bf16 v[76:79], v[174:177], v[214:217], v[76:79]
	v_mfma_f32_16x16x32_bf16 v[124:127], v[174:177], v[190:193], v[124:127]
	v_mfma_f32_16x16x32_bf16 v[124:127], v[170:173], v[186:189], v[124:127]
	v_mfma_f32_16x16x32_bf16 v[120:123], v[178:181], v[186:189], v[120:123]
	v_mfma_f32_16x16x32_bf16 v[120:123], v[182:185], v[190:193], v[120:123]
	v_mfma_f32_16x16x32_bf16 v[104:107], v[182:185], v[198:201], v[104:107]
	v_mfma_f32_16x16x32_bf16 v[104:107], v[178:181], v[194:197], v[104:107]
	v_mfma_f32_16x16x32_bf16 v[108:111], v[170:173], v[194:197], v[108:111]
	v_mfma_f32_16x16x32_bf16 v[108:111], v[174:177], v[198:201], v[108:111]
	v_mfma_f32_16x16x32_bf16 v[92:95], v[174:177], v[206:209], v[92:95]
	v_mfma_f32_16x16x32_bf16 v[92:95], v[170:173], v[202:205], v[92:95]
	v_mfma_f32_16x16x32_bf16 v[88:91], v[178:181], v[202:205], v[88:91]
	v_mfma_f32_16x16x32_bf16 v[88:91], v[182:185], v[206:209], v[88:91]
	v_mfma_f32_16x16x32_bf16 v[72:75], v[182:185], v[214:217], v[72:75]
	v_mfma_f32_16x16x32_bf16 v[72:75], v[178:181], v[210:213], v[72:75]
	s_setprio 0
	s_barrier
; #define PG8_STAGE(bufoff, gbase, voff) do { _Pragma("unroll") for (int _i = 0; _i < 2; ++_i) \
;         __builtin_amdgcn_global_load_lds((const unsigned*)((const char*)(gbase) + (voff)[_i]), (PG8_LAS unsigned*)(lds + (bufoff) + ldsw + _i * 8192), 16, 0, 0); } while (0)
; #define PG8_LDA(dst, b, h) do { _Pragma("unroll") for (int m = 0; m < 4; ++m) _Pragma("unroll") for (int k = 0; k < 2; ++k) dst[m][k] = *(const PG8_LAS bf16x8*)(lds + PG8_SA(b, h) + aoff + m * 2048 + k * 1024); } while (0)
; #define PG8_MMA(ai, bj, At, Bt) do { __builtin_amdgcn_s_setprio(1); _Pragma("unroll") for (int m = 0; m < 4; ++m) _Pragma("unroll") for (int n = 0; n < 2; ++n) _Pragma("unroll") for (int k = 0; k < 2; ++k) \
;         acc[ai][bj][m][n] = __builtin_amdgcn_mfma_f32_16x16x32_bf16(Bt[n][k], At[m][k], acc[ai][bj][m][n], 0, 0, 0); __builtin_amdgcn_s_setprio(0); } while (0)
; #define PG8_WAIT_V(n) asm volatile("s_waitcnt vmcnt(" #n ")" ::: "memory")
; #define PG8_WAIT_L(n) asm volatile("s_waitcnt lgkmcnt(" #n ")" ::: "memory")
; #define PG8_BAR __builtin_amdgcn_s_barrier()
; #define PG8_SCHED __builtin_amdgcn_sched_barrier(0)
; template <class Epi, class Sched, bool ALIGN_EPI = false, bool SP2 = false, bool ABLK = false, bool BBLK = false>
; __device__ __forceinline__ void gemm_phase(PG8_LAS unsigned char* lds, const Gemm g, const Sched& S, const Epi& E) {
;     ...
;         for (int t = 0; t < nt; t += 2) {
;             const bool last = (t == nt - 2);
;     ...
;             PG8_LDA(At, 1, 1); PG8_STAGE(PG8_SB(1, 0), b3, voffB); PG8_STAGE(PG8_SB(1, 1), b3 + hstepB, voffB); PG8_STAGE(PG8_SA(1, 0), a3, voffA);
;             PG8_WAIT_V(8); PG8_WAIT_L(0); PG8_BAR; PG8_MMA(1, 0, At, B0); PG8_MMA(1, 1, At, B1); PG8_BAR; PG8_SCHED;
	s_add_u32 s26, s24, 0x8000
	s_addc_u32 s27, s25, 0
	s_add_i32 s13, s13, s31
	s_mov_b32 m0, s13
	ds_read_b128 v[186:189], v161 offset:49152
	ds_read_b128 v[190:193], v161 offset:50176
	ds_read_b128 v[194:197], v161 offset:51200
	ds_read_b128 v[198:201], v161 offset:52224
	ds_read_b128 v[202:205], v161 offset:53248
	ds_read_b128 v[206:209], v161 offset:54272
	ds_read_b128 v[210:213], v161 offset:55296
	ds_read_b128 v[214:217], v161 offset:56320
	global_load_lds_dwordx4 v140, s[26:27]
	s_add_i32 m0, s13, 0x2000
	s_add_u32 s24, s24, 0xc000
	s_addc_u32 s25, s25, 0
	s_add_i32 s13, s68, s31
	global_load_lds_dwordx4 v136, s[26:27]
	s_mov_b32 m0, s13
	s_nop 0
	global_load_lds_dwordx4 v140, s[24:25]
	s_add_i32 m0, s13, 0x2000
	s_nop 0
	global_load_lds_dwordx4 v136, s[24:25]
	s_mov_b32 m0, s62
	s_nop 0
	global_load_lds_dwordx4 v142, s[22:23]
	s_mov_b32 m0, s63
	s_nop 0
	global_load_lds_dwordx4 v138, s[22:23]
	s_waitcnt vmcnt(8)
	s_waitcnt lgkmcnt(0)
	v_mfma_f32_16x16x32_bf16 v[68:71], v[152:155], v[186:189], v[68:71]
	v_mfma_f32_16x16x32_bf16 v[68:71], v[156:159], v[190:193], v[68:71]
	v_mfma_f32_16x16x32_bf16 v[64:67], v[166:169], v[190:193], v[64:67]
	v_mfma_f32_16x16x32_bf16 v[64:67], v[162:165], v[186:189], v[64:67]
	v_mfma_f32_16x16x32_bf16 v[48:51], v[162:165], v[194:197], v[48:51]
	v_mfma_f32_16x16x32_bf16 v[48:51], v[166:169], v[198:201], v[48:51]
	v_mfma_f32_16x16x32_bf16 v[52:55], v[156:159], v[198:201], v[52:55]
	v_mfma_f32_16x16x32_bf16 v[52:55], v[152:155], v[194:197], v[52:55]
	s_barrier
	s_setprio 1
	v_mfma_f32_16x16x32_bf16 v[32:35], v[152:155], v[202:205], v[32:35]
	v_mfma_f32_16x16x32_bf16 v[32:35], v[156:159], v[206:209], v[32:35]
	v_mfma_f32_16x16x32_bf16 v[28:31], v[166:169], v[206:209], v[28:31]
	v_mfma_f32_16x16x32_bf16 v[28:31], v[162:165], v[202:205], v[28:31]
	v_mfma_f32_16x16x32_bf16 v[12:15], v[162:165], v[210:213], v[12:15]
	v_mfma_f32_16x16x32_bf16 v[12:15], v[166:169], v[214:217], v[12:15]
	v_mfma_f32_16x16x32_bf16 v[16:19], v[156:159], v[214:217], v[16:19]
	v_mfma_f32_16x16x32_bf16 v[16:19], v[152:155], v[210:213], v[16:19]
	s_setprio 0
	s_setprio 1
	v_mfma_f32_16x16x32_bf16 v[8:11], v[170:173], v[210:213], v[8:11]
	v_mfma_f32_16x16x32_bf16 v[8:11], v[174:177], v[214:217], v[8:11]
	v_mfma_f32_16x16x32_bf16 v[60:63], v[174:177], v[190:193], v[60:63]
	v_mfma_f32_16x16x32_bf16 v[60:63], v[170:173], v[186:189], v[60:63]
	v_mfma_f32_16x16x32_bf16 v[56:59], v[178:181], v[186:189], v[56:59]
	v_mfma_f32_16x16x32_bf16 v[56:59], v[182:185], v[190:193], v[56:59]
	v_mfma_f32_16x16x32_bf16 v[40:43], v[182:185], v[198:201], v[40:43]
	v_mfma_f32_16x16x32_bf16 v[40:43], v[178:181], v[194:197], v[40:43]
	v_mfma_f32_16x16x32_bf16 v[44:47], v[170:173], v[194:197], v[44:47]
	v_mfma_f32_16x16x32_bf16 v[44:47], v[174:177], v[198:201], v[44:47]
	v_mfma_f32_16x16x32_bf16 v[24:27], v[174:177], v[206:209], v[24:27]
	v_mfma_f32_16x16x32_bf16 v[24:27], v[170:173], v[202:205], v[24:27]
	v_mfma_f32_16x16x32_bf16 v[20:23], v[178:181], v[202:205], v[20:23]
	v_mfma_f32_16x16x32_bf16 v[20:23], v[182:185], v[206:209], v[20:23]
	v_mfma_f32_16x16x32_bf16 v[4:7], v[182:185], v[214:217], v[4:7]
	v_mfma_f32_16x16x32_bf16 v[4:7], v[178:181], v[210:213], v[4:7]
	s_setprio 0
	s_barrier
	s_add_i32 vcc_hi, vcc_hi, 2
	s_add_u32 s20, s20, 0x10000
	s_addc_u32 s21, s21, 0
	s_add_u32 s77, s77, 0x10000
	s_addc_u32 vcc_lo, vcc_lo, 0
	s_cmp_gt_u32 vcc_hi, 29
	s_cbranch_scc0 .LBB0_185
	s_and_b64 vcc, exec, s[4:5]
	s_cbranch_vccz .LBB0_188
	s_barrier

; #define PG8_STAGE(bufoff, gbase, voff) do { _Pragma("unroll") for (int _i = 0; _i < 2; ++_i) \
;         __builtin_amdgcn_global_load_lds((const unsigned*)((const char*)(gbase) + (voff)[_i]), (PG8_LAS unsigned*)(lds + (bufoff) + ldsw + _i * 8192), 16, 0, 0); } while (0)
; #define PG8_LDA(dst, b, h) do { _Pragma("unroll") for (int m = 0; m < 4; ++m) _Pragma("unroll") for (int k = 0; k < 2; ++k) dst[m][k] = *(const PG8_LAS bf16x8*)(lds + PG8_SA(b, h) + aoff + m * 2048 + k * 1024); } while (0)
; #define PG8_LDB(dst, b, h) do { _Pragma("unroll") for (int n = 0; n < 2; ++n) _Pragma("unroll") for (int k = 0; k < 2; ++k) dst[n][k] = *(const PG8_LAS bf16x8*)(lds + PG8_SB(b, h) + boff + n * 2048 + k * 1024); } while (0)
; #define PG8_MMA(ai, bj, At, Bt) do { __builtin_amdgcn_s_setprio(1); _Pragma("unroll") for (int m = 0; m < 4; ++m) _Pragma("unroll") for (int n = 0; n < 2; ++n) _Pragma("unroll") for (int k = 0; k < 2; ++k) \
;         acc[ai][bj][m][n] = __builtin_amdgcn_mfma_f32_16x16x32_bf16(Bt[n][k], At[m][k], acc[ai][bj][m][n], 0, 0, 0); __builtin_amdgcn_s_setprio(0); } while (0)
; #define PG8_WAIT_V(n) asm volatile("s_waitcnt vmcnt(" #n ")" ::: "memory")
; #define PG8_BAR __builtin_amdgcn_s_barrier()
; template <class Epi, class Sched, bool ALIGN_EPI = false, bool SP2 = false, bool ABLK = false, bool BBLK = false>
; __device__ __forceinline__ void gemm_phase(PG8_LAS unsigned char* lds, const Gemm g, const Sched& S, const Epi& E) {
;     ...
;             const bool last = (t == nt - 2);
;             const char* a1 = cA + (size_t)(t + 1) * kstepA;
;             const char* a2 = last ? nA : cA + (size_t)(t + 2) * kstepA; const char* b2 = last ? nB : cB + (size_t)(t + 2) * kstepB;
;             const char* a3 = a2 + kstepA; const char* b3 = b2 + kstepB;
;             if (last && has_next) S.a_ready(nxt);
;             if constexpr (SP2) {
;             PG8_LDB(B0, 0, 0); PG8_LDB(B1, 0, 1); PG8_SCHED; PG8_LDA(At, 0, 0); PG8_STAGE(PG8_SA(1, 1), a1 + hstepA, voffA);
;             PG8_WAIT_V(8); PG8_WAIT_L(0); PG8_BAR; PG8_MMA(0, 0, At, B0); PG8_MMA(0, 1, At, B1); PG8_BAR; PG8_SCHED;
;             PG8_LDA(At, 0, 1); PG8_STAGE(PG8_SB(0, 0), b2, voffB); PG8_STAGE(PG8_SB(0, 1), b2 + hstepB, voffB); PG8_STAGE(PG8_SA(0, 0), a2, voffA);
;             PG8_WAIT_V(8); PG8_WAIT_L(0); PG8_BAR; PG8_MMA(1, 0, At, B0); PG8_MMA(1, 1, At, B1); PG8_BAR; PG8_SCHED;
.LBB0_439:
	s_add_u32 s16, s10, 0x4000
	s_addc_u32 s17, s11, 0
	s_cmpk_eq_i32 s13, 0x54
	s_cselect_b32 s20, s0, s16
	s_cselect_b32 s21, s1, s17
	s_cselect_b32 s18, s8, vcc_lo
	s_cselect_b32 s19, s9, vcc_hi
	s_add_u32 s16, s20, 0x8000
	s_addc_u32 s17, s21, 0
	s_add_i32 s68, 0, 0x10000
	v_add_u32_e32 v36, s68, v148
	s_add_i32 s88, 0, 0x14000
	ds_read_b128 v[152:155], v36
	ds_read_b128 v[156:159], v36 offset:1024
	ds_read_b128 v[160:163], v36 offset:2048
	ds_read_b128 v[164:167], v36 offset:3072
	v_add_u32_e32 v36, s88, v148
	ds_read_b128 v[168:171], v36
	ds_read_b128 v[172:175], v36 offset:1024
	ds_read_b128 v[176:179], v36 offset:2048
	ds_read_b128 v[180:183], v36 offset:3072
	s_add_i32 m0, s27, 0xc000
	ds_read_b128 v[184:187], v150
	ds_read_b128 v[188:191], v150 offset:1024
	ds_read_b128 v[192:195], v150 offset:2048
	ds_read_b128 v[196:199], v150 offset:3072
	ds_read_b128 v[200:203], v150 offset:4096
	ds_read_b128 v[204:207], v150 offset:5120
	ds_read_b128 v[208:211], v150 offset:6144
	ds_read_b128 v[212:215], v150 offset:7168
	global_load_lds_dwordx4 v144, s[10:11]
	s_add_i32 m0, s27, 0xe000
	s_nop 0
	global_load_lds_dwordx4 v146, s[10:11]
	s_waitcnt vmcnt(8)
	s_waitcnt lgkmcnt(0)
	v_mfma_f32_16x16x32_bf16 v[132:135], v[152:155], v[184:187], v[132:135]
	v_mfma_f32_16x16x32_bf16 v[132:135], v[156:159], v[188:191], v[132:135]
	v_mfma_f32_16x16x32_bf16 v[128:131], v[164:167], v[188:191], v[128:131]
	v_mfma_f32_16x16x32_bf16 v[128:131], v[160:163], v[184:187], v[128:131]
	v_mfma_f32_16x16x32_bf16 v[120:123], v[160:163], v[192:195], v[120:123]
	v_mfma_f32_16x16x32_bf16 v[120:123], v[164:167], v[196:199], v[120:123]
	v_mfma_f32_16x16x32_bf16 v[124:127], v[156:159], v[196:199], v[124:127]
	v_mfma_f32_16x16x32_bf16 v[124:127], v[152:155], v[192:195], v[124:127]
	s_barrier
	s_setprio 1
	v_mfma_f32_16x16x32_bf16 v[108:111], v[152:155], v[200:203], v[108:111]
	v_mfma_f32_16x16x32_bf16 v[108:111], v[156:159], v[204:207], v[108:111]
	v_mfma_f32_16x16x32_bf16 v[104:107], v[164:167], v[204:207], v[104:107]
	v_mfma_f32_16x16x32_bf16 v[104:107], v[160:163], v[200:203], v[104:107]
	v_mfma_f32_16x16x32_bf16 v[88:91], v[160:163], v[208:211], v[88:91]
	v_mfma_f32_16x16x32_bf16 v[88:91], v[164:167], v[212:215], v[88:91]
	v_mfma_f32_16x16x32_bf16 v[92:95], v[156:159], v[212:215], v[92:95]
	v_mfma_f32_16x16x32_bf16 v[92:95], v[152:155], v[208:211], v[92:95]
	s_setprio 0
	s_setprio 1
	v_mfma_f32_16x16x32_bf16 v[76:79], v[168:171], v[208:211], v[76:79]
	v_mfma_f32_16x16x32_bf16 v[76:79], v[172:175], v[212:215], v[76:79]
	v_mfma_f32_16x16x32_bf16 v[116:119], v[172:175], v[188:191], v[116:119]
	v_mfma_f32_16x16x32_bf16 v[116:119], v[168:171], v[184:187], v[116:119]
	v_mfma_f32_16x16x32_bf16 v[112:115], v[176:179], v[184:187], v[112:115]
	v_mfma_f32_16x16x32_bf16 v[112:115], v[180:183], v[188:191], v[112:115]
	v_mfma_f32_16x16x32_bf16 v[96:99], v[180:183], v[196:199], v[96:99]
	v_mfma_f32_16x16x32_bf16 v[96:99], v[176:179], v[192:195], v[96:99]
	v_mfma_f32_16x16x32_bf16 v[100:103], v[168:171], v[192:195], v[100:103]
	v_mfma_f32_16x16x32_bf16 v[100:103], v[172:175], v[196:199], v[100:103]
	v_mfma_f32_16x16x32_bf16 v[84:87], v[172:175], v[204:207], v[84:87]
	v_mfma_f32_16x16x32_bf16 v[84:87], v[168:171], v[200:203], v[84:87]
	v_mfma_f32_16x16x32_bf16 v[80:83], v[176:179], v[200:203], v[80:83]
	v_mfma_f32_16x16x32_bf16 v[80:83], v[180:183], v[204:207], v[80:83]
	v_mfma_f32_16x16x32_bf16 v[72:75], v[180:183], v[212:215], v[72:75]
	v_mfma_f32_16x16x32_bf16 v[72:75], v[176:179], v[208:211], v[72:75]
	s_setprio 0
	s_barrier
	s_add_i32 s68, s68, s24
	s_mov_b32 m0, s68
	ds_read_b128 v[184:187], v150 offset:16384
	ds_read_b128 v[188:191], v150 offset:17408
	ds_read_b128 v[192:195], v150 offset:18432
	ds_read_b128 v[196:199], v150 offset:19456
	ds_read_b128 v[200:203], v150 offset:20480
	ds_read_b128 v[204:207], v150 offset:21504
	ds_read_b128 v[208:211], v150 offset:22528
	ds_read_b128 v[212:215], v150 offset:23552
	global_load_lds_dwordx4 v138, s[18:19]
	s_add_i32 m0, s68, 0x2000
	s_add_u32 s68, s18, 0x4000
	s_addc_u32 s69, s19, 0
	s_add_i32 s88, s88, s24
	global_load_lds_dwordx4 v142, s[18:19]
	s_mov_b32 m0, s88
	s_nop 0
	global_load_lds_dwordx4 v138, s[68:69]
	s_add_i32 m0, s88, 0x2000
	s_nop 0
	global_load_lds_dwordx4 v142, s[68:69]
	s_mov_b32 m0, s27
	s_nop 0
	global_load_lds_dwordx4 v136, s[20:21]
	s_mov_b32 m0, s28
	s_nop 0
	global_load_lds_dwordx4 v140, s[20:21]
	s_waitcnt vmcnt(8)
	s_waitcnt lgkmcnt(0)
	v_mfma_f32_16x16x32_bf16 v[68:71], v[152:155], v[184:187], v[68:71]
	v_mfma_f32_16x16x32_bf16 v[68:71], v[156:159], v[188:191], v[68:71]
	v_mfma_f32_16x16x32_bf16 v[64:67], v[164:167], v[188:191], v[64:67]
	v_mfma_f32_16x16x32_bf16 v[64:67], v[160:163], v[184:187], v[64:67]
	v_mfma_f32_16x16x32_bf16 v[56:59], v[160:163], v[192:195], v[56:59]
	v_mfma_f32_16x16x32_bf16 v[56:59], v[164:167], v[196:199], v[56:59]
	v_mfma_f32_16x16x32_bf16 v[60:63], v[156:159], v[196:199], v[60:63]
	v_mfma_f32_16x16x32_bf16 v[60:63], v[152:155], v[192:195], v[60:63]
	s_barrier
; #define PG8_STAGE(bufoff, gbase, voff) do { _Pragma("unroll") for (int _i = 0; _i < 2; ++_i) \
;         __builtin_amdgcn_global_load_lds((const unsigned*)((const char*)(gbase) + (voff)[_i]), (PG8_LAS unsigned*)(lds + (bufoff) + ldsw + _i * 8192), 16, 0, 0); } while (0)
; #define PG8_LDA(dst, b, h) do { _Pragma("unroll") for (int m = 0; m < 4; ++m) _Pragma("unroll") for (int k = 0; k < 2; ++k) dst[m][k] = *(const PG8_LAS bf16x8*)(lds + PG8_SA(b, h) + aoff + m * 2048 + k * 1024); } while (0)
; #define PG8_LDB(dst, b, h) do { _Pragma("unroll") for (int n = 0; n < 2; ++n) _Pragma("unroll") for (int k = 0; k < 2; ++k) dst[n][k] = *(const PG8_LAS bf16x8*)(lds + PG8_SB(b, h) + boff + n * 2048 + k * 1024); } while (0)
; #define PG8_MMA(ai, bj, At, Bt) do { __builtin_amdgcn_s_setprio(1); _Pragma("unroll") for (int m = 0; m < 4; ++m) _Pragma("unroll") for (int n = 0; n < 2; ++n) _Pragma("unroll") for (int k = 0; k < 2; ++k) \
;         acc[ai][bj][m][n] = __builtin_amdgcn_mfma_f32_16x16x32_bf16(Bt[n][k], At[m][k], acc[ai][bj][m][n], 0, 0, 0); __builtin_amdgcn_s_setprio(0); } while (0)
; #define PG8_WAIT_V(n) asm volatile("s_waitcnt vmcnt(" #n ")" ::: "memory")
; #define PG8_WAIT_L(n) asm volatile("s_waitcnt lgkmcnt(" #n ")" ::: "memory")
; #define PG8_BAR __builtin_amdgcn_s_barrier()
; #define PG8_SCHED __builtin_amdgcn_sched_barrier(0)
; template <class Epi, class Sched, bool ALIGN_EPI = false, bool SP2 = false, bool ABLK = false, bool BBLK = false>
; __device__ __forceinline__ void gemm_phase(PG8_LAS unsigned char* lds, const Gemm g, const Sched& S, const Epi& E) {
;     ...
;             PG8_WAIT_V(8); PG8_WAIT_L(0); PG8_BAR; PG8_MMA(1, 0, At, B0); PG8_MMA(1, 1, At, B1); PG8_BAR; PG8_SCHED;
;             PG8_LDB(B0, 1, 0); PG8_LDB(B1, 1, 1); PG8_SCHED; PG8_LDA(At, 1, 0); PG8_STAGE(PG8_SA(0, 1), a2 + hstepA, voffA);
;             PG8_WAIT_V(8); PG8_WAIT_L(0); PG8_BAR; PG8_MMA(0, 0, At, B0); PG8_MMA(0, 1, At, B1); PG8_BAR; PG8_SCHED;
	s_setprio 1
	v_mfma_f32_16x16x32_bf16 v[44:47], v[152:155], v[200:203], v[44:47]
	v_mfma_f32_16x16x32_bf16 v[44:47], v[156:159], v[204:207], v[44:47]
	v_mfma_f32_16x16x32_bf16 v[40:43], v[164:167], v[204:207], v[40:43]
	v_mfma_f32_16x16x32_bf16 v[40:43], v[160:163], v[200:203], v[40:43]
	v_mfma_f32_16x16x32_bf16 v[20:23], v[160:163], v[208:211], v[20:23]
	v_mfma_f32_16x16x32_bf16 v[20:23], v[164:167], v[212:215], v[20:23]
	v_mfma_f32_16x16x32_bf16 v[24:27], v[156:159], v[212:215], v[24:27]
	v_mfma_f32_16x16x32_bf16 v[24:27], v[152:155], v[208:211], v[24:27]
	s_setprio 0
	s_setprio 1
	v_mfma_f32_16x16x32_bf16 v[8:11], v[168:171], v[208:211], v[8:11]
	v_mfma_f32_16x16x32_bf16 v[8:11], v[172:175], v[212:215], v[8:11]
	v_mfma_f32_16x16x32_bf16 v[52:55], v[172:175], v[188:191], v[52:55]
	v_mfma_f32_16x16x32_bf16 v[52:55], v[168:171], v[184:187], v[52:55]
	v_mfma_f32_16x16x32_bf16 v[48:51], v[176:179], v[184:187], v[48:51]
	v_mfma_f32_16x16x32_bf16 v[48:51], v[180:183], v[188:191], v[48:51]
	v_mfma_f32_16x16x32_bf16 v[28:31], v[180:183], v[196:199], v[28:31]
	v_mfma_f32_16x16x32_bf16 v[28:31], v[176:179], v[192:195], v[28:31]
	v_mfma_f32_16x16x32_bf16 v[32:35], v[168:171], v[192:195], v[32:35]
	v_mfma_f32_16x16x32_bf16 v[32:35], v[172:175], v[196:199], v[32:35]
	v_mfma_f32_16x16x32_bf16 v[16:19], v[172:175], v[204:207], v[16:19]
	v_mfma_f32_16x16x32_bf16 v[16:19], v[168:171], v[200:203], v[16:19]
	v_mfma_f32_16x16x32_bf16 v[12:15], v[176:179], v[200:203], v[12:15]
	v_mfma_f32_16x16x32_bf16 v[12:15], v[180:183], v[204:207], v[12:15]
	v_mfma_f32_16x16x32_bf16 v[4:7], v[180:183], v[212:215], v[4:7]
	v_mfma_f32_16x16x32_bf16 v[4:7], v[176:179], v[208:211], v[4:7]
	s_setprio 0
	s_barrier
	s_add_i32 s68, 0, 0x18000
	v_add_u32_e32 v36, s68, v148
	s_add_i32 s69, 0, 0x1c000
	ds_read_b128 v[152:155], v36
	ds_read_b128 v[156:159], v36 offset:1024
	ds_read_b128 v[160:163], v36 offset:2048
	ds_read_b128 v[164:167], v36 offset:3072
	v_add_u32_e32 v36, s69, v148
	ds_read_b128 v[168:171], v36
	ds_read_b128 v[172:175], v36 offset:1024
	ds_read_b128 v[176:179], v36 offset:2048
	ds_read_b128 v[180:183], v36 offset:3072
	s_add_u32 s20, s20, 0x4000
	s_addc_u32 s21, s21, 0
	s_mov_b32 m0, s29
	ds_read_b128 v[184:187], v150 offset:32768
	ds_read_b128 v[188:191], v150 offset:33792
	ds_read_b128 v[192:195], v150 offset:34816
	ds_read_b128 v[196:199], v150 offset:35840
	ds_read_b128 v[200:203], v150 offset:36864
	ds_read_b128 v[204:207], v150 offset:37888
	ds_read_b128 v[208:211], v150 offset:38912
	ds_read_b128 v[212:215], v150 offset:39936
	global_load_lds_dwordx4 v136, s[20:21]
	s_mov_b32 m0, s30
	s_nop 0
	global_load_lds_dwordx4 v140, s[20:21]
	s_waitcnt vmcnt(8)
	s_waitcnt lgkmcnt(0)
	v_mfma_f32_16x16x32_bf16 v[132:135], v[152:155], v[184:187], v[132:135]
	v_mfma_f32_16x16x32_bf16 v[132:135], v[156:159], v[188:191], v[132:135]
	v_mfma_f32_16x16x32_bf16 v[128:131], v[164:167], v[188:191], v[128:131]
	v_mfma_f32_16x16x32_bf16 v[128:131], v[160:163], v[184:187], v[128:131]
	v_mfma_f32_16x16x32_bf16 v[120:123], v[160:163], v[192:195], v[120:123]
	v_mfma_f32_16x16x32_bf16 v[120:123], v[164:167], v[196:199], v[120:123]
	v_mfma_f32_16x16x32_bf16 v[124:127], v[156:159], v[196:199], v[124:127]
	v_mfma_f32_16x16x32_bf16 v[124:127], v[152:155], v[192:195], v[124:127]
	s_barrier
	s_setprio 1
	v_mfma_f32_16x16x32_bf16 v[108:111], v[152:155], v[200:203], v[108:111]
	v_mfma_f32_16x16x32_bf16 v[108:111], v[156:159], v[204:207], v[108:111]
	v_mfma_f32_16x16x32_bf16 v[104:107], v[164:167], v[204:207], v[104:107]
	v_mfma_f32_16x16x32_bf16 v[104:107], v[160:163], v[200:203], v[104:107]
	v_mfma_f32_16x16x32_bf16 v[88:91], v[160:163], v[208:211], v[88:91]
	v_mfma_f32_16x16x32_bf16 v[88:91], v[164:167], v[212:215], v[88:91]
	v_mfma_f32_16x16x32_bf16 v[92:95], v[156:159], v[212:215], v[92:95]
	v_mfma_f32_16x16x32_bf16 v[92:95], v[152:155], v[208:211], v[92:95]
	s_setprio 0
	s_setprio 1
	v_mfma_f32_16x16x32_bf16 v[76:79], v[168:171], v[208:211], v[76:79]
	v_mfma_f32_16x16x32_bf16 v[76:79], v[172:175], v[212:215], v[76:79]
	v_mfma_f32_16x16x32_bf16 v[116:119], v[172:175], v[188:191], v[116:119]
	v_mfma_f32_16x16x32_bf16 v[116:119], v[168:171], v[184:187], v[116:119]
	v_mfma_f32_16x16x32_bf16 v[112:115], v[176:179], v[184:187], v[112:115]
	v_mfma_f32_16x16x32_bf16 v[112:115], v[180:183], v[188:191], v[112:115]
	v_mfma_f32_16x16x32_bf16 v[96:99], v[180:183], v[196:199], v[96:99]
	v_mfma_f32_16x16x32_bf16 v[96:99], v[176:179], v[192:195], v[96:99]
	v_mfma_f32_16x16x32_bf16 v[100:103], v[168:171], v[192:195], v[100:103]
	v_mfma_f32_16x16x32_bf16 v[100:103], v[172:175], v[196:199], v[100:103]
	v_mfma_f32_16x16x32_bf16 v[84:87], v[172:175], v[204:207], v[84:87]
	v_mfma_f32_16x16x32_bf16 v[84:87], v[168:171], v[200:203], v[84:87]
	v_mfma_f32_16x16x32_bf16 v[80:83], v[176:179], v[200:203], v[80:83]
	v_mfma_f32_16x16x32_bf16 v[80:83], v[180:183], v[204:207], v[80:83]
	v_mfma_f32_16x16x32_bf16 v[72:75], v[180:183], v[212:215], v[72:75]
	v_mfma_f32_16x16x32_bf16 v[72:75], v[176:179], v[208:211], v[72:75]
	s_setprio 0
	s_barrier
; #define PG8_STAGE(bufoff, gbase, voff) do { _Pragma("unroll") for (int _i = 0; _i < 2; ++_i) \
;         __builtin_amdgcn_global_load_lds((const unsigned*)((const char*)(gbase) + (voff)[_i]), (PG8_LAS unsigned*)(lds + (bufoff) + ldsw + _i * 8192), 16, 0, 0); } while (0)
; #define PG8_LDA(dst, b, h) do { _Pragma("unroll") for (int m = 0; m < 4; ++m) _Pragma("unroll") for (int k = 0; k < 2; ++k) dst[m][k] = *(const PG8_LAS bf16x8*)(lds + PG8_SA(b, h) + aoff + m * 2048 + k * 1024); } while (0)
; #define PG8_MMA(ai, bj, At, Bt) do { __builtin_amdgcn_s_setprio(1); _Pragma("unroll") for (int m = 0; m < 4; ++m) _Pragma("unroll") for (int n = 0; n < 2; ++n) _Pragma("unroll") for (int k = 0; k < 2; ++k) \
;         acc[ai][bj][m][n] = __builtin_amdgcn_mfma_f32_16x16x32_bf16(Bt[n][k], At[m][k], acc[ai][bj][m][n], 0, 0, 0); __builtin_amdgcn_s_setprio(0); } while (0)
; #define PG8_WAIT_V(n) asm volatile("s_waitcnt vmcnt(" #n ")" ::: "memory")
; #define PG8_WAIT_L(n) asm volatile("s_waitcnt lgkmcnt(" #n ")" ::: "memory")
; #define PG8_BAR __builtin_amdgcn_s_barrier()
; #define PG8_SCHED __builtin_amdgcn_sched_barrier(0)
; template <class Epi, class Sched, bool ALIGN_EPI = false, bool SP2 = false, bool ABLK = false, bool BBLK = false>
; __device__ __forceinline__ void gemm_phase(PG8_LAS unsigned char* lds, const Gemm g, const Sched& S, const Epi& E) {
;     ...
;         for (int t = 0; t < nt; t += 2) {
;             const bool last = (t == nt - 2);
;     ...
;             PG8_LDA(At, 1, 1); PG8_STAGE(PG8_SB(1, 0), b3, voffB); PG8_STAGE(PG8_SB(1, 1), b3 + hstepB, voffB); PG8_STAGE(PG8_SA(1, 0), a3, voffA);
;             PG8_WAIT_V(8); PG8_WAIT_L(0); PG8_BAR; PG8_MMA(1, 0, At, B0); PG8_MMA(1, 1, At, B1); PG8_BAR; PG8_SCHED;
	s_add_u32 s20, s18, 0x8000
	s_addc_u32 s21, s19, 0
	s_add_i32 s68, s68, s24
	s_mov_b32 m0, s68
	ds_read_b128 v[184:187], v150 offset:49152
	ds_read_b128 v[188:191], v150 offset:50176
	ds_read_b128 v[192:195], v150 offset:51200
	ds_read_b128 v[196:199], v150 offset:52224
	ds_read_b128 v[200:203], v150 offset:53248
	ds_read_b128 v[204:207], v150 offset:54272
	ds_read_b128 v[208:211], v150 offset:55296
	ds_read_b128 v[212:215], v150 offset:56320
	global_load_lds_dwordx4 v138, s[20:21]
	s_add_i32 m0, s68, 0x2000
	s_add_u32 s18, s18, 0xc000
	s_addc_u32 s19, s19, 0
	global_load_lds_dwordx4 v142, s[20:21]
	s_add_i32 s20, s69, s24
	s_mov_b32 m0, s20
	s_nop 0
	global_load_lds_dwordx4 v138, s[18:19]
	s_add_i32 m0, s20, 0x2000
	s_nop 0
	global_load_lds_dwordx4 v142, s[18:19]
	s_mov_b32 m0, s35
	s_nop 0
	global_load_lds_dwordx4 v136, s[16:17]
	s_mov_b32 m0, s70
	s_nop 0
	global_load_lds_dwordx4 v140, s[16:17]
	s_waitcnt vmcnt(8)
	s_waitcnt lgkmcnt(0)
	v_mfma_f32_16x16x32_bf16 v[68:71], v[152:155], v[184:187], v[68:71]
	v_mfma_f32_16x16x32_bf16 v[68:71], v[156:159], v[188:191], v[68:71]
	v_mfma_f32_16x16x32_bf16 v[64:67], v[164:167], v[188:191], v[64:67]
	v_mfma_f32_16x16x32_bf16 v[64:67], v[160:163], v[184:187], v[64:67]
	v_mfma_f32_16x16x32_bf16 v[56:59], v[160:163], v[192:195], v[56:59]
	v_mfma_f32_16x16x32_bf16 v[56:59], v[164:167], v[196:199], v[56:59]
	v_mfma_f32_16x16x32_bf16 v[60:63], v[156:159], v[196:199], v[60:63]
	v_mfma_f32_16x16x32_bf16 v[60:63], v[152:155], v[192:195], v[60:63]
	s_barrier
	s_setprio 1
	v_mfma_f32_16x16x32_bf16 v[44:47], v[152:155], v[200:203], v[44:47]
	v_mfma_f32_16x16x32_bf16 v[44:47], v[156:159], v[204:207], v[44:47]
	v_mfma_f32_16x16x32_bf16 v[40:43], v[164:167], v[204:207], v[40:43]
	v_mfma_f32_16x16x32_bf16 v[40:43], v[160:163], v[200:203], v[40:43]
	v_mfma_f32_16x16x32_bf16 v[20:23], v[160:163], v[208:211], v[20:23]
	v_mfma_f32_16x16x32_bf16 v[20:23], v[164:167], v[212:215], v[20:23]
	v_mfma_f32_16x16x32_bf16 v[24:27], v[156:159], v[212:215], v[24:27]
	v_mfma_f32_16x16x32_bf16 v[24:27], v[152:155], v[208:211], v[24:27]
	s_setprio 0
	s_setprio 1
	v_mfma_f32_16x16x32_bf16 v[8:11], v[168:171], v[208:211], v[8:11]
	v_mfma_f32_16x16x32_bf16 v[8:11], v[172:175], v[212:215], v[8:11]
	v_mfma_f32_16x16x32_bf16 v[52:55], v[172:175], v[188:191], v[52:55]
	v_mfma_f32_16x16x32_bf16 v[52:55], v[168:171], v[184:187], v[52:55]
	v_mfma_f32_16x16x32_bf16 v[48:51], v[176:179], v[184:187], v[48:51]
	v_mfma_f32_16x16x32_bf16 v[48:51], v[180:183], v[188:191], v[48:51]
	v_mfma_f32_16x16x32_bf16 v[28:31], v[180:183], v[196:199], v[28:31]
	v_mfma_f32_16x16x32_bf16 v[28:31], v[176:179], v[192:195], v[28:31]
	v_mfma_f32_16x16x32_bf16 v[32:35], v[168:171], v[192:195], v[32:35]
	v_mfma_f32_16x16x32_bf16 v[32:35], v[172:175], v[196:199], v[32:35]
	v_mfma_f32_16x16x32_bf16 v[16:19], v[172:175], v[204:207], v[16:19]
	v_mfma_f32_16x16x32_bf16 v[16:19], v[168:171], v[200:203], v[16:19]
	v_mfma_f32_16x16x32_bf16 v[12:15], v[176:179], v[200:203], v[12:15]
	v_mfma_f32_16x16x32_bf16 v[12:15], v[180:183], v[204:207], v[12:15]
	v_mfma_f32_16x16x32_bf16 v[4:7], v[180:183], v[212:215], v[4:7]
	v_mfma_f32_16x16x32_bf16 v[4:7], v[176:179], v[208:211], v[4:7]
	s_setprio 0
	s_barrier
	s_add_i32 s13, s13, 2
	s_add_u32 s10, s10, 0x10000
	s_addc_u32 s11, s11, 0
	s_add_u32 vcc_lo, vcc_lo, 0x10000
	s_addc_u32 vcc_hi, vcc_hi, 0
	s_cmpk_gt_u32 s13, 0x55
	s_cbranch_scc0 .LBB0_439
	s_and_b64 vcc, exec, s[6:7]
	s_cbranch_vccz .LBB0_442
	s_barrier

; #define PG8_STAGE(bufoff, gbase, voff) do { _Pragma("unroll") for (int _i = 0; _i < 2; ++_i) \
;         __builtin_amdgcn_global_load_lds((const unsigned*)((const char*)(gbase) + (voff)[_i]), (PG8_LAS unsigned*)(lds + (bufoff) + ldsw + _i * 8192), 16, 0, 0); } while (0)
; #define PG8_LDA(dst, b, h) do { _Pragma("unroll") for (int m = 0; m < 4; ++m) _Pragma("unroll") for (int k = 0; k < 2; ++k) dst[m][k] = *(const PG8_LAS bf16x8*)(lds + PG8_SA(b, h) + aoff + m * 2048 + k * 1024); } while (0)
; #define PG8_LDB(dst, b, h) do { _Pragma("unroll") for (int n = 0; n < 2; ++n) _Pragma("unroll") for (int k = 0; k < 2; ++k) dst[n][k] = *(const PG8_LAS bf16x8*)(lds + PG8_SB(b, h) + boff + n * 2048 + k * 1024); } while (0)
; #define PG8_MMA(ai, bj, At, Bt) do { __builtin_amdgcn_s_setprio(1); _Pragma("unroll") for (int m = 0; m < 4; ++m) _Pragma("unroll") for (int n = 0; n < 2; ++n) _Pragma("unroll") for (int k = 0; k < 2; ++k) \
;         acc[ai][bj][m][n] = __builtin_amdgcn_mfma_f32_16x16x32_bf16(Bt[n][k], At[m][k], acc[ai][bj][m][n], 0, 0, 0); __builtin_amdgcn_s_setprio(0); } while (0)
; #define PG8_WAIT_V(n) asm volatile("s_waitcnt vmcnt(" #n ")" ::: "memory")
; #define PG8_BAR __builtin_amdgcn_s_barrier()
; template <class Epi, class Sched, bool ALIGN_EPI = false, bool SP2 = false, bool ABLK = false, bool BBLK = false>
; __device__ __forceinline__ void gemm_phase(PG8_LAS unsigned char* lds, const Gemm g, const Sched& S, const Epi& E) {
;     ...
;             const bool last = (t == nt - 2);
;             const char* a1 = cA + (size_t)(t + 1) * kstepA;
;             const char* a2 = last ? nA : cA + (size_t)(t + 2) * kstepA; const char* b2 = last ? nB : cB + (size_t)(t + 2) * kstepB;
;             const char* a3 = a2 + kstepA; const char* b3 = b2 + kstepB;
;             if (last && has_next) S.a_ready(nxt);
;             if constexpr (SP2) {
;             PG8_LDB(B0, 0, 0); PG8_LDB(B1, 0, 1); PG8_SCHED; PG8_LDA(At, 0, 0); PG8_STAGE(PG8_SA(1, 1), a1 + hstepA, voffA);
;             PG8_WAIT_V(8); PG8_WAIT_L(0); PG8_BAR; PG8_MMA(0, 0, At, B0); PG8_MMA(0, 1, At, B1); PG8_BAR; PG8_SCHED;
;             PG8_LDA(At, 0, 1); PG8_STAGE(PG8_SB(0, 0), b2, voffB); PG8_STAGE(PG8_SB(0, 1), b2 + hstepB, voffB); PG8_STAGE(PG8_SA(0, 0), a2, voffA);
;             PG8_WAIT_V(8); PG8_WAIT_L(0); PG8_BAR; PG8_MMA(1, 0, At, B0); PG8_MMA(1, 1, At, B1); PG8_BAR; PG8_SCHED;
.LBB0_916:
	s_add_u32 s22, s20, 0x4000
	s_addc_u32 s23, s21, 0
	s_cmp_eq_u32 s13, 28
	s_cselect_b32 s26, s19, s22
	s_cselect_b32 s27, s1, s23
	s_cselect_b32 s24, s65, s70
	s_cselect_b32 s25, s9, s71
	s_add_u32 s22, s26, 0x8000
	s_addc_u32 s23, s27, 0
	s_add_i32 s68, 0, 0x10000
	v_add_u32_e32 v36, s68, v155
	s_add_i32 s77, 0, 0x14000
	ds_read_b128 v[150:153], v36
	ds_read_b128 v[158:161], v36 offset:1024
	ds_read_b128 v[162:165], v36 offset:2048
	ds_read_b128 v[166:169], v36 offset:3072
	v_add_u32_e32 v36, s77, v155
	ds_read_b128 v[170:173], v36
	ds_read_b128 v[174:177], v36 offset:1024
	ds_read_b128 v[178:181], v36 offset:2048
	ds_read_b128 v[182:185], v36 offset:3072
	s_add_i32 m0, s31, 0xc000
	ds_read_b128 v[186:189], v157
	ds_read_b128 v[190:193], v157 offset:1024
	ds_read_b128 v[194:197], v157 offset:2048
	ds_read_b128 v[198:201], v157 offset:3072
	ds_read_b128 v[202:205], v157 offset:4096
	ds_read_b128 v[206:209], v157 offset:5120
	ds_read_b128 v[210:213], v157 offset:6144
	ds_read_b128 v[214:217], v157 offset:7168
	global_load_lds_dwordx4 v146, s[20:21]
	s_add_i32 m0, s31, 0xe000
	s_nop 0
	global_load_lds_dwordx4 v148, s[20:21]
	s_waitcnt vmcnt(8)
	s_waitcnt lgkmcnt(0)
	v_mfma_f32_16x16x32_bf16 v[132:135], v[150:153], v[186:189], v[132:135]
	v_mfma_f32_16x16x32_bf16 v[132:135], v[158:161], v[190:193], v[132:135]
	v_mfma_f32_16x16x32_bf16 v[128:131], v[166:169], v[190:193], v[128:131]
	v_mfma_f32_16x16x32_bf16 v[128:131], v[162:165], v[186:189], v[128:131]
	v_mfma_f32_16x16x32_bf16 v[116:119], v[162:165], v[194:197], v[116:119]
	v_mfma_f32_16x16x32_bf16 v[116:119], v[166:169], v[198:201], v[116:119]
	v_mfma_f32_16x16x32_bf16 v[124:127], v[158:161], v[198:201], v[124:127]
	v_mfma_f32_16x16x32_bf16 v[124:127], v[150:153], v[194:197], v[124:127]
	s_barrier
	s_setprio 1
	v_mfma_f32_16x16x32_bf16 v[108:111], v[150:153], v[202:205], v[108:111]
	v_mfma_f32_16x16x32_bf16 v[108:111], v[158:161], v[206:209], v[108:111]
	v_mfma_f32_16x16x32_bf16 v[100:103], v[166:169], v[206:209], v[100:103]
	v_mfma_f32_16x16x32_bf16 v[100:103], v[162:165], v[202:205], v[100:103]
	v_mfma_f32_16x16x32_bf16 v[84:87], v[162:165], v[210:213], v[84:87]
	v_mfma_f32_16x16x32_bf16 v[84:87], v[166:169], v[214:217], v[84:87]
	v_mfma_f32_16x16x32_bf16 v[92:95], v[158:161], v[214:217], v[92:95]
	v_mfma_f32_16x16x32_bf16 v[92:95], v[150:153], v[210:213], v[92:95]
	s_setprio 0
	s_setprio 1
	v_mfma_f32_16x16x32_bf16 v[76:79], v[170:173], v[210:213], v[76:79]
	v_mfma_f32_16x16x32_bf16 v[76:79], v[174:177], v[214:217], v[76:79]
	v_mfma_f32_16x16x32_bf16 v[120:123], v[174:177], v[190:193], v[120:123]
	v_mfma_f32_16x16x32_bf16 v[120:123], v[170:173], v[186:189], v[120:123]
	v_mfma_f32_16x16x32_bf16 v[112:115], v[178:181], v[186:189], v[112:115]
	v_mfma_f32_16x16x32_bf16 v[112:115], v[182:185], v[190:193], v[112:115]
	v_mfma_f32_16x16x32_bf16 v[96:99], v[182:185], v[198:201], v[96:99]
	v_mfma_f32_16x16x32_bf16 v[96:99], v[178:181], v[194:197], v[96:99]
	v_mfma_f32_16x16x32_bf16 v[104:107], v[170:173], v[194:197], v[104:107]
	v_mfma_f32_16x16x32_bf16 v[104:107], v[174:177], v[198:201], v[104:107]
	v_mfma_f32_16x16x32_bf16 v[88:91], v[174:177], v[206:209], v[88:91]
	v_mfma_f32_16x16x32_bf16 v[88:91], v[170:173], v[202:205], v[88:91]
	v_mfma_f32_16x16x32_bf16 v[80:83], v[178:181], v[202:205], v[80:83]
	v_mfma_f32_16x16x32_bf16 v[80:83], v[182:185], v[206:209], v[80:83]
	v_mfma_f32_16x16x32_bf16 v[72:75], v[182:185], v[214:217], v[72:75]
	v_mfma_f32_16x16x32_bf16 v[72:75], v[178:181], v[210:213], v[72:75]
	s_setprio 0
	s_barrier
	s_add_i32 s68, s68, s29
	s_mov_b32 m0, s68
	ds_read_b128 v[186:189], v157 offset:16384
	ds_read_b128 v[190:193], v157 offset:17408
	ds_read_b128 v[194:197], v157 offset:18432
	ds_read_b128 v[198:201], v157 offset:19456
	ds_read_b128 v[202:205], v157 offset:20480
	ds_read_b128 v[206:209], v157 offset:21504
	ds_read_b128 v[210:213], v157 offset:22528
	ds_read_b128 v[214:217], v157 offset:23552
	global_load_lds_dwordx4 v140, s[24:25]
	s_add_i32 m0, s68, 0x2000
	s_add_u32 s68, s24, 0x4000
	s_addc_u32 s69, s25, 0
	s_add_i32 s77, s77, s29
	global_load_lds_dwordx4 v136, s[24:25]
	s_mov_b32 m0, s77
	s_nop 0
	global_load_lds_dwordx4 v140, s[68:69]
	s_add_i32 m0, s77, 0x2000
	s_nop 0
	global_load_lds_dwordx4 v136, s[68:69]
	s_mov_b32 m0, s31
	s_nop 0
	global_load_lds_dwordx4 v142, s[26:27]
	s_mov_b32 m0, s34
	s_nop 0
	global_load_lds_dwordx4 v138, s[26:27]
	s_waitcnt vmcnt(8)
	s_waitcnt lgkmcnt(0)
	v_mfma_f32_16x16x32_bf16 v[68:71], v[150:153], v[186:189], v[68:71]
	v_mfma_f32_16x16x32_bf16 v[68:71], v[158:161], v[190:193], v[68:71]
	v_mfma_f32_16x16x32_bf16 v[64:67], v[166:169], v[190:193], v[64:67]
	v_mfma_f32_16x16x32_bf16 v[64:67], v[162:165], v[186:189], v[64:67]
	v_mfma_f32_16x16x32_bf16 v[52:55], v[162:165], v[194:197], v[52:55]
	v_mfma_f32_16x16x32_bf16 v[52:55], v[166:169], v[198:201], v[52:55]
	v_mfma_f32_16x16x32_bf16 v[60:63], v[158:161], v[198:201], v[60:63]
	v_mfma_f32_16x16x32_bf16 v[60:63], v[150:153], v[194:197], v[60:63]
	s_barrier
; #define PG8_STAGE(bufoff, gbase, voff) do { _Pragma("unroll") for (int _i = 0; _i < 2; ++_i) \
;         __builtin_amdgcn_global_load_lds((const unsigned*)((const char*)(gbase) + (voff)[_i]), (PG8_LAS unsigned*)(lds + (bufoff) + ldsw + _i * 8192), 16, 0, 0); } while (0)
; #define PG8_LDA(dst, b, h) do { _Pragma("unroll") for (int m = 0; m < 4; ++m) _Pragma("unroll") for (int k = 0; k < 2; ++k) dst[m][k] = *(const PG8_LAS bf16x8*)(lds + PG8_SA(b, h) + aoff + m * 2048 + k * 1024); } while (0)
; #define PG8_LDB(dst, b, h) do { _Pragma("unroll") for (int n = 0; n < 2; ++n) _Pragma("unroll") for (int k = 0; k < 2; ++k) dst[n][k] = *(const PG8_LAS bf16x8*)(lds + PG8_SB(b, h) + boff + n * 2048 + k * 1024); } while (0)
; #define PG8_MMA(ai, bj, At, Bt) do { __builtin_amdgcn_s_setprio(1); _Pragma("unroll") for (int m = 0; m < 4; ++m) _Pragma("unroll") for (int n = 0; n < 2; ++n) _Pragma("unroll") for (int k = 0; k < 2; ++k) \
;         acc[ai][bj][m][n] = __builtin_amdgcn_mfma_f32_16x16x32_bf16(Bt[n][k], At[m][k], acc[ai][bj][m][n], 0, 0, 0); __builtin_amdgcn_s_setprio(0); } while (0)
; #define PG8_WAIT_V(n) asm volatile("s_waitcnt vmcnt(" #n ")" ::: "memory")
; #define PG8_WAIT_L(n) asm volatile("s_waitcnt lgkmcnt(" #n ")" ::: "memory")
; #define PG8_BAR __builtin_amdgcn_s_barrier()
; #define PG8_SCHED __builtin_amdgcn_sched_barrier(0)
; template <class Epi, class Sched, bool ALIGN_EPI = false, bool SP2 = false, bool ABLK = false, bool BBLK = false>
; __device__ __forceinline__ void gemm_phase(PG8_LAS unsigned char* lds, const Gemm g, const Sched& S, const Epi& E) {
;     ...
;             PG8_WAIT_V(8); PG8_WAIT_L(0); PG8_BAR; PG8_MMA(1, 0, At, B0); PG8_MMA(1, 1, At, B1); PG8_BAR; PG8_SCHED;
;             PG8_LDB(B0, 1, 0); PG8_LDB(B1, 1, 1); PG8_SCHED; PG8_LDA(At, 1, 0); PG8_STAGE(PG8_SA(0, 1), a2 + hstepA, voffA);
;             PG8_WAIT_V(8); PG8_WAIT_L(0); PG8_BAR; PG8_MMA(0, 0, At, B0); PG8_MMA(0, 1, At, B1); PG8_BAR; PG8_SCHED;
	s_setprio 1
	v_mfma_f32_16x16x32_bf16 v[44:47], v[150:153], v[202:205], v[44:47]
	v_mfma_f32_16x16x32_bf16 v[44:47], v[158:161], v[206:209], v[44:47]
	v_mfma_f32_16x16x32_bf16 v[32:35], v[166:169], v[206:209], v[32:35]
	v_mfma_f32_16x16x32_bf16 v[32:35], v[162:165], v[202:205], v[32:35]
	v_mfma_f32_16x16x32_bf16 v[16:19], v[162:165], v[210:213], v[16:19]
	v_mfma_f32_16x16x32_bf16 v[16:19], v[166:169], v[214:217], v[16:19]
	v_mfma_f32_16x16x32_bf16 v[24:27], v[158:161], v[214:217], v[24:27]
	v_mfma_f32_16x16x32_bf16 v[24:27], v[150:153], v[210:213], v[24:27]
	s_setprio 0
	s_setprio 1
	v_mfma_f32_16x16x32_bf16 v[8:11], v[170:173], v[210:213], v[8:11]
	v_mfma_f32_16x16x32_bf16 v[8:11], v[174:177], v[214:217], v[8:11]
	v_mfma_f32_16x16x32_bf16 v[56:59], v[174:177], v[190:193], v[56:59]
	v_mfma_f32_16x16x32_bf16 v[56:59], v[170:173], v[186:189], v[56:59]
	v_mfma_f32_16x16x32_bf16 v[48:51], v[178:181], v[186:189], v[48:51]
	v_mfma_f32_16x16x32_bf16 v[48:51], v[182:185], v[190:193], v[48:51]
	v_mfma_f32_16x16x32_bf16 v[28:31], v[182:185], v[198:201], v[28:31]
	v_mfma_f32_16x16x32_bf16 v[28:31], v[178:181], v[194:197], v[28:31]
	v_mfma_f32_16x16x32_bf16 v[40:43], v[170:173], v[194:197], v[40:43]
	v_mfma_f32_16x16x32_bf16 v[40:43], v[174:177], v[198:201], v[40:43]
	v_mfma_f32_16x16x32_bf16 v[20:23], v[174:177], v[206:209], v[20:23]
	v_mfma_f32_16x16x32_bf16 v[20:23], v[170:173], v[202:205], v[20:23]
	v_mfma_f32_16x16x32_bf16 v[12:15], v[178:181], v[202:205], v[12:15]
	v_mfma_f32_16x16x32_bf16 v[12:15], v[182:185], v[206:209], v[12:15]
	v_mfma_f32_16x16x32_bf16 v[4:7], v[182:185], v[214:217], v[4:7]
	v_mfma_f32_16x16x32_bf16 v[4:7], v[178:181], v[210:213], v[4:7]
	s_setprio 0
	s_barrier
	s_add_i32 s68, 0, 0x18000
	v_add_u32_e32 v36, s68, v155
	s_add_i32 s69, 0, 0x1c000
	ds_read_b128 v[150:153], v36
	ds_read_b128 v[158:161], v36 offset:1024
	ds_read_b128 v[162:165], v36 offset:2048
	ds_read_b128 v[166:169], v36 offset:3072
	v_add_u32_e32 v36, s69, v155
	ds_read_b128 v[170:173], v36
	ds_read_b128 v[174:177], v36 offset:1024
	ds_read_b128 v[178:181], v36 offset:2048
	ds_read_b128 v[182:185], v36 offset:3072
	s_add_u32 s26, s26, 0x4000
	s_addc_u32 s27, s27, 0
	s_mov_b32 m0, s35
	ds_read_b128 v[186:189], v157 offset:32768
	ds_read_b128 v[190:193], v157 offset:33792
	ds_read_b128 v[194:197], v157 offset:34816
	ds_read_b128 v[198:201], v157 offset:35840
	ds_read_b128 v[202:205], v157 offset:36864
	ds_read_b128 v[206:209], v157 offset:37888
	ds_read_b128 v[210:213], v157 offset:38912
	ds_read_b128 v[214:217], v157 offset:39936
	global_load_lds_dwordx4 v142, s[26:27]
	s_mov_b32 m0, s36
	s_nop 0
	global_load_lds_dwordx4 v138, s[26:27]
	s_waitcnt vmcnt(8)
	s_waitcnt lgkmcnt(0)
	v_mfma_f32_16x16x32_bf16 v[132:135], v[150:153], v[186:189], v[132:135]
	v_mfma_f32_16x16x32_bf16 v[132:135], v[158:161], v[190:193], v[132:135]
	v_mfma_f32_16x16x32_bf16 v[128:131], v[166:169], v[190:193], v[128:131]
	v_mfma_f32_16x16x32_bf16 v[128:131], v[162:165], v[186:189], v[128:131]
	v_mfma_f32_16x16x32_bf16 v[116:119], v[162:165], v[194:197], v[116:119]
	v_mfma_f32_16x16x32_bf16 v[116:119], v[166:169], v[198:201], v[116:119]
	v_mfma_f32_16x16x32_bf16 v[124:127], v[158:161], v[198:201], v[124:127]
	v_mfma_f32_16x16x32_bf16 v[124:127], v[150:153], v[194:197], v[124:127]
	s_barrier
	s_setprio 1
	v_mfma_f32_16x16x32_bf16 v[108:111], v[150:153], v[202:205], v[108:111]
	v_mfma_f32_16x16x32_bf16 v[108:111], v[158:161], v[206:209], v[108:111]
	v_mfma_f32_16x16x32_bf16 v[100:103], v[166:169], v[206:209], v[100:103]
	v_mfma_f32_16x16x32_bf16 v[100:103], v[162:165], v[202:205], v[100:103]
	v_mfma_f32_16x16x32_bf16 v[84:87], v[162:165], v[210:213], v[84:87]
	v_mfma_f32_16x16x32_bf16 v[84:87], v[166:169], v[214:217], v[84:87]
	v_mfma_f32_16x16x32_bf16 v[92:95], v[158:161], v[214:217], v[92:95]
	v_mfma_f32_16x16x32_bf16 v[92:95], v[150:153], v[210:213], v[92:95]
	s_setprio 0
	s_setprio 1
	v_mfma_f32_16x16x32_bf16 v[76:79], v[170:173], v[210:213], v[76:79]
	v_mfma_f32_16x16x32_bf16 v[76:79], v[174:177], v[214:217], v[76:79]
	v_mfma_f32_16x16x32_bf16 v[120:123], v[174:177], v[190:193], v[120:123]
	v_mfma_f32_16x16x32_bf16 v[120:123], v[170:173], v[186:189], v[120:123]
	v_mfma_f32_16x16x32_bf16 v[112:115], v[178:181], v[186:189], v[112:115]
	v_mfma_f32_16x16x32_bf16 v[112:115], v[182:185], v[190:193], v[112:115]
	v_mfma_f32_16x16x32_bf16 v[96:99], v[182:185], v[198:201], v[96:99]
	v_mfma_f32_16x16x32_bf16 v[96:99], v[178:181], v[194:197], v[96:99]
	v_mfma_f32_16x16x32_bf16 v[104:107], v[170:173], v[194:197], v[104:107]
	v_mfma_f32_16x16x32_bf16 v[104:107], v[174:177], v[198:201], v[104:107]
	v_mfma_f32_16x16x32_bf16 v[88:91], v[174:177], v[206:209], v[88:91]
	v_mfma_f32_16x16x32_bf16 v[88:91], v[170:173], v[202:205], v[88:91]
	v_mfma_f32_16x16x32_bf16 v[80:83], v[178:181], v[202:205], v[80:83]
	v_mfma_f32_16x16x32_bf16 v[80:83], v[182:185], v[206:209], v[80:83]
	v_mfma_f32_16x16x32_bf16 v[72:75], v[182:185], v[214:217], v[72:75]
	v_mfma_f32_16x16x32_bf16 v[72:75], v[178:181], v[210:213], v[72:75]
	s_setprio 0
	s_barrier
; #define PG8_STAGE(bufoff, gbase, voff) do { _Pragma("unroll") for (int _i = 0; _i < 2; ++_i) \
;         __builtin_amdgcn_global_load_lds((const unsigned*)((const char*)(gbase) + (voff)[_i]), (PG8_LAS unsigned*)(lds + (bufoff) + ldsw + _i * 8192), 16, 0, 0); } while (0)
; #define PG8_LDA(dst, b, h) do { _Pragma("unroll") for (int m = 0; m < 4; ++m) _Pragma("unroll") for (int k = 0; k < 2; ++k) dst[m][k] = *(const PG8_LAS bf16x8*)(lds + PG8_SA(b, h) + aoff + m * 2048 + k * 1024); } while (0)
; #define PG8_MMA(ai, bj, At, Bt) do { __builtin_amdgcn_s_setprio(1); _Pragma("unroll") for (int m = 0; m < 4; ++m) _Pragma("unroll") for (int n = 0; n < 2; ++n) _Pragma("unroll") for (int k = 0; k < 2; ++k) \
;         acc[ai][bj][m][n] = __builtin_amdgcn_mfma_f32_16x16x32_bf16(Bt[n][k], At[m][k], acc[ai][bj][m][n], 0, 0, 0); __builtin_amdgcn_s_setprio(0); } while (0)
; #define PG8_WAIT_V(n) asm volatile("s_waitcnt vmcnt(" #n ")" ::: "memory")
; #define PG8_WAIT_L(n) asm volatile("s_waitcnt lgkmcnt(" #n ")" ::: "memory")
; #define PG8_BAR __builtin_amdgcn_s_barrier()
; #define PG8_SCHED __builtin_amdgcn_sched_barrier(0)
; template <class Epi, class Sched, bool ALIGN_EPI = false, bool SP2 = false, bool ABLK = false, bool BBLK = false>
; __device__ __forceinline__ void gemm_phase(PG8_LAS unsigned char* lds, const Gemm g, const Sched& S, const Epi& E) {
;     ...
;         for (int t = 0; t < nt; t += 2) {
;             const bool last = (t == nt - 2);
;     ...
;             PG8_LDA(At, 1, 1); PG8_STAGE(PG8_SB(1, 0), b3, voffB); PG8_STAGE(PG8_SB(1, 1), b3 + hstepB, voffB); PG8_STAGE(PG8_SA(1, 0), a3, voffA);
;             PG8_WAIT_V(8); PG8_WAIT_L(0); PG8_BAR; PG8_MMA(1, 0, At, B0); PG8_MMA(1, 1, At, B1); PG8_BAR; PG8_SCHED;
	s_add_u32 s26, s24, 0x8000
	s_addc_u32 s27, s25, 0
	s_add_i32 s68, s68, s29
	s_mov_b32 m0, s68
	ds_read_b128 v[186:189], v157 offset:49152
	ds_read_b128 v[190:193], v157 offset:50176
	ds_read_b128 v[194:197], v157 offset:51200
	ds_read_b128 v[198:201], v157 offset:52224
	ds_read_b128 v[202:205], v157 offset:53248
	ds_read_b128 v[206:209], v157 offset:54272
	ds_read_b128 v[210:213], v157 offset:55296
	ds_read_b128 v[214:217], v157 offset:56320
	global_load_lds_dwordx4 v140, s[26:27]
	s_add_i32 m0, s68, 0x2000
	s_add_u32 s24, s24, 0xc000
	s_addc_u32 s25, s25, 0
	global_load_lds_dwordx4 v136, s[26:27]
	s_add_i32 s26, s69, s29
	s_mov_b32 m0, s26
	s_nop 0
	global_load_lds_dwordx4 v140, s[24:25]
	s_add_i32 m0, s26, 0x2000
	s_nop 0
	global_load_lds_dwordx4 v136, s[24:25]
	s_mov_b32 m0, s37
	s_nop 0
	global_load_lds_dwordx4 v142, s[22:23]
	s_mov_b32 m0, s62
	s_nop 0
	global_load_lds_dwordx4 v138, s[22:23]
	s_waitcnt vmcnt(8)
	s_waitcnt lgkmcnt(0)
	v_mfma_f32_16x16x32_bf16 v[68:71], v[150:153], v[186:189], v[68:71]
	v_mfma_f32_16x16x32_bf16 v[68:71], v[158:161], v[190:193], v[68:71]
	v_mfma_f32_16x16x32_bf16 v[64:67], v[166:169], v[190:193], v[64:67]
	v_mfma_f32_16x16x32_bf16 v[64:67], v[162:165], v[186:189], v[64:67]
	v_mfma_f32_16x16x32_bf16 v[52:55], v[162:165], v[194:197], v[52:55]
	v_mfma_f32_16x16x32_bf16 v[52:55], v[166:169], v[198:201], v[52:55]
	v_mfma_f32_16x16x32_bf16 v[60:63], v[158:161], v[198:201], v[60:63]
	v_mfma_f32_16x16x32_bf16 v[60:63], v[150:153], v[194:197], v[60:63]
	s_barrier
	s_setprio 1
	v_mfma_f32_16x16x32_bf16 v[44:47], v[150:153], v[202:205], v[44:47]
	v_mfma_f32_16x16x32_bf16 v[44:47], v[158:161], v[206:209], v[44:47]
	v_mfma_f32_16x16x32_bf16 v[32:35], v[166:169], v[206:209], v[32:35]
	v_mfma_f32_16x16x32_bf16 v[32:35], v[162:165], v[202:205], v[32:35]
	v_mfma_f32_16x16x32_bf16 v[16:19], v[162:165], v[210:213], v[16:19]
	v_mfma_f32_16x16x32_bf16 v[16:19], v[166:169], v[214:217], v[16:19]
	v_mfma_f32_16x16x32_bf16 v[24:27], v[158:161], v[214:217], v[24:27]
	v_mfma_f32_16x16x32_bf16 v[24:27], v[150:153], v[210:213], v[24:27]
	s_setprio 0
	s_setprio 1
	v_mfma_f32_16x16x32_bf16 v[8:11], v[170:173], v[210:213], v[8:11]
	v_mfma_f32_16x16x32_bf16 v[8:11], v[174:177], v[214:217], v[8:11]
	v_mfma_f32_16x16x32_bf16 v[56:59], v[174:177], v[190:193], v[56:59]
	v_mfma_f32_16x16x32_bf16 v[56:59], v[170:173], v[186:189], v[56:59]
	v_mfma_f32_16x16x32_bf16 v[48:51], v[178:181], v[186:189], v[48:51]
	v_mfma_f32_16x16x32_bf16 v[48:51], v[182:185], v[190:193], v[48:51]
	v_mfma_f32_16x16x32_bf16 v[28:31], v[182:185], v[198:201], v[28:31]
	v_mfma_f32_16x16x32_bf16 v[28:31], v[178:181], v[194:197], v[28:31]
	v_mfma_f32_16x16x32_bf16 v[40:43], v[170:173], v[194:197], v[40:43]
	v_mfma_f32_16x16x32_bf16 v[40:43], v[174:177], v[198:201], v[40:43]
	v_mfma_f32_16x16x32_bf16 v[20:23], v[174:177], v[206:209], v[20:23]
	v_mfma_f32_16x16x32_bf16 v[20:23], v[170:173], v[202:205], v[20:23]
	v_mfma_f32_16x16x32_bf16 v[12:15], v[178:181], v[202:205], v[12:15]
	v_mfma_f32_16x16x32_bf16 v[12:15], v[182:185], v[206:209], v[12:15]
	v_mfma_f32_16x16x32_bf16 v[4:7], v[182:185], v[214:217], v[4:7]
	v_mfma_f32_16x16x32_bf16 v[4:7], v[178:181], v[210:213], v[4:7]
	s_setprio 0
	s_barrier
	s_add_i32 s13, s13, 2
	s_add_u32 s20, s20, 0x10000
	s_addc_u32 s21, s21, 0
	s_add_u32 s70, s70, 0x10000
	s_addc_u32 s71, s71, 0
	s_cmp_gt_u32 s13, 29
	s_cbranch_scc0 .LBB0_916
	s_and_b64 vcc, exec, s[6:7]
	s_cbranch_vccz .LBB0_919
	s_barrier

; #define PG8_STAGE(bufoff, gbase, voff) do { _Pragma("unroll") for (int _i = 0; _i < 2; ++_i) \
;         __builtin_amdgcn_global_load_lds((const unsigned*)((const char*)(gbase) + (voff)[_i]), (PG8_LAS unsigned*)(lds + (bufoff) + ldsw + _i * 8192), 16, 0, 0); } while (0)
; #define PG8_LDA(dst, b, h) do { _Pragma("unroll") for (int m = 0; m < 4; ++m) _Pragma("unroll") for (int k = 0; k < 2; ++k) dst[m][k] = *(const PG8_LAS bf16x8*)(lds + PG8_SA(b, h) + aoff + m * 2048 + k * 1024); } while (0)
; #define PG8_LDB(dst, b, h) do { _Pragma("unroll") for (int n = 0; n < 2; ++n) _Pragma("unroll") for (int k = 0; k < 2; ++k) dst[n][k] = *(const PG8_LAS bf16x8*)(lds + PG8_SB(b, h) + boff + n * 2048 + k * 1024); } while (0)
; #define PG8_MMA(ai, bj, At, Bt) do { __builtin_amdgcn_s_setprio(1); _Pragma("unroll") for (int m = 0; m < 4; ++m) _Pragma("unroll") for (int n = 0; n < 2; ++n) _Pragma("unroll") for (int k = 0; k < 2; ++k) \
;         acc[ai][bj][m][n] = __builtin_amdgcn_mfma_f32_16x16x32_bf16(Bt[n][k], At[m][k], acc[ai][bj][m][n], 0, 0, 0); __builtin_amdgcn_s_setprio(0); } while (0)
; #define PG8_WAIT_V(n) asm volatile("s_waitcnt vmcnt(" #n ")" ::: "memory")
; #define PG8_BAR __builtin_amdgcn_s_barrier()
; template <class Epi, class Sched, bool ALIGN_EPI = false, bool SP2 = false, bool ABLK = false, bool BBLK = false>
; __device__ __forceinline__ void gemm_phase(PG8_LAS unsigned char* lds, const Gemm g, const Sched& S, const Epi& E) {
;     ...
;             const bool last = (t == nt - 2);
;             const char* a1 = cA + (size_t)(t + 1) * kstepA;
;             const char* a2 = last ? nA : cA + (size_t)(t + 2) * kstepA; const char* b2 = last ? nB : cB + (size_t)(t + 2) * kstepB;
;             const char* a3 = a2 + kstepA; const char* b3 = b2 + kstepB;
;             if (last && has_next) S.a_ready(nxt);
;             if constexpr (SP2) {
;             PG8_LDB(B0, 0, 0); PG8_LDB(B1, 0, 1); PG8_SCHED; PG8_LDA(At, 0, 0); PG8_STAGE(PG8_SA(1, 1), a1 + hstepA, voffA);
;             PG8_WAIT_V(8); PG8_WAIT_L(0); PG8_BAR; PG8_MMA(0, 0, At, B0); PG8_MMA(0, 1, At, B1); PG8_BAR; PG8_SCHED;
;             PG8_LDA(At, 0, 1); PG8_STAGE(PG8_SB(0, 0), b2, voffB); PG8_STAGE(PG8_SB(0, 1), b2 + hstepB, voffB); PG8_STAGE(PG8_SA(0, 0), a2, voffA);
;             PG8_WAIT_V(8); PG8_WAIT_L(0); PG8_BAR; PG8_MMA(1, 0, At, B0); PG8_MMA(1, 1, At, B1); PG8_BAR; PG8_SCHED;
.LBB0_2111:
	s_add_u32 s24, s22, 0x4000
	s_addc_u32 s25, s23, 0
	s_cmp_eq_u32 s13, 28
	s_cselect_b32 s28, s17, s24
	s_cselect_b32 s29, s12, s25
	s_cselect_b32 s26, s77, s82
	s_cselect_b32 s27, s11, vcc_lo
	s_add_u32 s24, s28, 0x8000
	s_addc_u32 s25, s29, 0
	s_add_i32 s68, 0, 0x10000
	v_add_u32_e32 v151, s68, v148
	s_add_i32 s88, 0, 0x14000
	ds_read_b128 v[36:39], v151
	ds_read_b128 v[152:155], v151 offset:1024
	ds_read_b128 v[156:159], v151 offset:2048
	ds_read_b128 v[160:163], v151 offset:3072
	v_add_u32_e32 v151, s88, v148
	ds_read_b128 v[164:167], v151
	ds_read_b128 v[168:171], v151 offset:1024
	ds_read_b128 v[172:175], v151 offset:2048
	ds_read_b128 v[176:179], v151 offset:3072
	s_add_i32 m0, s9, 0xc000
	ds_read_b128 v[180:183], v150
	ds_read_b128 v[184:187], v150 offset:1024
	ds_read_b128 v[188:191], v150 offset:2048
	ds_read_b128 v[192:195], v150 offset:3072
	ds_read_b128 v[196:199], v150 offset:4096
	ds_read_b128 v[200:203], v150 offset:5120
	ds_read_b128 v[204:207], v150 offset:6144
	ds_read_b128 v[208:211], v150 offset:7168
	global_load_lds_dwordx4 v144, s[22:23]
	s_add_i32 m0, s9, 0xe000
	s_nop 0
	global_load_lds_dwordx4 v146, s[22:23]
	s_waitcnt vmcnt(8)
	s_waitcnt lgkmcnt(0)
	v_mfma_f32_16x16x32_bf16 v[132:135], v[36:39], v[180:183], v[132:135]
	v_mfma_f32_16x16x32_bf16 v[132:135], v[152:155], v[184:187], v[132:135]
	v_mfma_f32_16x16x32_bf16 v[128:131], v[160:163], v[184:187], v[128:131]
	v_mfma_f32_16x16x32_bf16 v[128:131], v[156:159], v[180:183], v[128:131]
	v_mfma_f32_16x16x32_bf16 v[120:123], v[156:159], v[188:191], v[120:123]
	v_mfma_f32_16x16x32_bf16 v[120:123], v[160:163], v[192:195], v[120:123]
	v_mfma_f32_16x16x32_bf16 v[124:127], v[152:155], v[192:195], v[124:127]
	v_mfma_f32_16x16x32_bf16 v[124:127], v[36:39], v[188:191], v[124:127]
	s_barrier
	s_setprio 1
	v_mfma_f32_16x16x32_bf16 v[108:111], v[36:39], v[196:199], v[108:111]
	v_mfma_f32_16x16x32_bf16 v[108:111], v[152:155], v[200:203], v[108:111]
	v_mfma_f32_16x16x32_bf16 v[104:107], v[160:163], v[200:203], v[104:107]
	v_mfma_f32_16x16x32_bf16 v[104:107], v[156:159], v[196:199], v[104:107]
	v_mfma_f32_16x16x32_bf16 v[88:91], v[156:159], v[204:207], v[88:91]
	v_mfma_f32_16x16x32_bf16 v[88:91], v[160:163], v[208:211], v[88:91]
	v_mfma_f32_16x16x32_bf16 v[92:95], v[152:155], v[208:211], v[92:95]
	v_mfma_f32_16x16x32_bf16 v[92:95], v[36:39], v[204:207], v[92:95]
	s_setprio 0
	s_setprio 1
	v_mfma_f32_16x16x32_bf16 v[76:79], v[164:167], v[204:207], v[76:79]
	v_mfma_f32_16x16x32_bf16 v[76:79], v[168:171], v[208:211], v[76:79]
	v_mfma_f32_16x16x32_bf16 v[116:119], v[168:171], v[184:187], v[116:119]
	v_mfma_f32_16x16x32_bf16 v[116:119], v[164:167], v[180:183], v[116:119]
	v_mfma_f32_16x16x32_bf16 v[112:115], v[172:175], v[180:183], v[112:115]
	v_mfma_f32_16x16x32_bf16 v[112:115], v[176:179], v[184:187], v[112:115]
	v_mfma_f32_16x16x32_bf16 v[96:99], v[176:179], v[192:195], v[96:99]
	v_mfma_f32_16x16x32_bf16 v[96:99], v[172:175], v[188:191], v[96:99]
	v_mfma_f32_16x16x32_bf16 v[100:103], v[164:167], v[188:191], v[100:103]
	v_mfma_f32_16x16x32_bf16 v[100:103], v[168:171], v[192:195], v[100:103]
	v_mfma_f32_16x16x32_bf16 v[84:87], v[168:171], v[200:203], v[84:87]
	v_mfma_f32_16x16x32_bf16 v[84:87], v[164:167], v[196:199], v[84:87]
	v_mfma_f32_16x16x32_bf16 v[80:83], v[172:175], v[196:199], v[80:83]
	v_mfma_f32_16x16x32_bf16 v[80:83], v[176:179], v[200:203], v[80:83]
	v_mfma_f32_16x16x32_bf16 v[72:75], v[176:179], v[208:211], v[72:75]
	v_mfma_f32_16x16x32_bf16 v[72:75], v[172:175], v[204:207], v[72:75]
	s_setprio 0
	s_barrier
	s_add_i32 s68, s68, s34
	s_mov_b32 m0, s68
	ds_read_b128 v[180:183], v150 offset:16384
	ds_read_b128 v[184:187], v150 offset:17408
	ds_read_b128 v[188:191], v150 offset:18432
	ds_read_b128 v[192:195], v150 offset:19456
	ds_read_b128 v[196:199], v150 offset:20480
	ds_read_b128 v[200:203], v150 offset:21504
	ds_read_b128 v[204:207], v150 offset:22528
	ds_read_b128 v[208:211], v150 offset:23552
	global_load_lds_dwordx4 v138, s[26:27]
	s_add_i32 m0, s68, 0x2000
	s_add_u32 s68, s26, 0x4000
	s_addc_u32 s69, s27, 0
	s_add_i32 s88, s88, s34
	global_load_lds_dwordx4 v142, s[26:27]
	s_mov_b32 m0, s88
	s_nop 0
	global_load_lds_dwordx4 v138, s[68:69]
	s_add_i32 m0, s88, 0x2000
	s_nop 0
	global_load_lds_dwordx4 v142, s[68:69]
	s_mov_b32 m0, s9
	s_nop 0
	global_load_lds_dwordx4 v136, s[28:29]
	s_mov_b32 m0, s35
	s_nop 0
	global_load_lds_dwordx4 v140, s[28:29]
	s_waitcnt vmcnt(8)
	s_waitcnt lgkmcnt(0)
	v_mfma_f32_16x16x32_bf16 v[68:71], v[36:39], v[180:183], v[68:71]
	v_mfma_f32_16x16x32_bf16 v[68:71], v[152:155], v[184:187], v[68:71]
	v_mfma_f32_16x16x32_bf16 v[64:67], v[160:163], v[184:187], v[64:67]
	v_mfma_f32_16x16x32_bf16 v[64:67], v[156:159], v[180:183], v[64:67]
	v_mfma_f32_16x16x32_bf16 v[56:59], v[156:159], v[188:191], v[56:59]
	v_mfma_f32_16x16x32_bf16 v[56:59], v[160:163], v[192:195], v[56:59]
	v_mfma_f32_16x16x32_bf16 v[60:63], v[152:155], v[192:195], v[60:63]
	v_mfma_f32_16x16x32_bf16 v[60:63], v[36:39], v[188:191], v[60:63]
	s_barrier
; #define PG8_STAGE(bufoff, gbase, voff) do { _Pragma("unroll") for (int _i = 0; _i < 2; ++_i) \
;         __builtin_amdgcn_global_load_lds((const unsigned*)((const char*)(gbase) + (voff)[_i]), (PG8_LAS unsigned*)(lds + (bufoff) + ldsw + _i * 8192), 16, 0, 0); } while (0)
; #define PG8_LDA(dst, b, h) do { _Pragma("unroll") for (int m = 0; m < 4; ++m) _Pragma("unroll") for (int k = 0; k < 2; ++k) dst[m][k] = *(const PG8_LAS bf16x8*)(lds + PG8_SA(b, h) + aoff + m * 2048 + k * 1024); } while (0)
; #define PG8_LDB(dst, b, h) do { _Pragma("unroll") for (int n = 0; n < 2; ++n) _Pragma("unroll") for (int k = 0; k < 2; ++k) dst[n][k] = *(const PG8_LAS bf16x8*)(lds + PG8_SB(b, h) + boff + n * 2048 + k * 1024); } while (0)
; #define PG8_MMA(ai, bj, At, Bt) do { __builtin_amdgcn_s_setprio(1); _Pragma("unroll") for (int m = 0; m < 4; ++m) _Pragma("unroll") for (int n = 0; n < 2; ++n) _Pragma("unroll") for (int k = 0; k < 2; ++k) \
;         acc[ai][bj][m][n] = __builtin_amdgcn_mfma_f32_16x16x32_bf16(Bt[n][k], At[m][k], acc[ai][bj][m][n], 0, 0, 0); __builtin_amdgcn_s_setprio(0); } while (0)
; #define PG8_WAIT_V(n) asm volatile("s_waitcnt vmcnt(" #n ")" ::: "memory")
; #define PG8_WAIT_L(n) asm volatile("s_waitcnt lgkmcnt(" #n ")" ::: "memory")
; #define PG8_BAR __builtin_amdgcn_s_barrier()
; #define PG8_SCHED __builtin_amdgcn_sched_barrier(0)
; template <class Epi, class Sched, bool ALIGN_EPI = false, bool SP2 = false, bool ABLK = false, bool BBLK = false>
; __device__ __forceinline__ void gemm_phase(PG8_LAS unsigned char* lds, const Gemm g, const Sched& S, const Epi& E) {
;     ...
;             PG8_WAIT_V(8); PG8_WAIT_L(0); PG8_BAR; PG8_MMA(1, 0, At, B0); PG8_MMA(1, 1, At, B1); PG8_BAR; PG8_SCHED;
;             PG8_LDB(B0, 1, 0); PG8_LDB(B1, 1, 1); PG8_SCHED; PG8_LDA(At, 1, 0); PG8_STAGE(PG8_SA(0, 1), a2 + hstepA, voffA);
;             PG8_WAIT_V(8); PG8_WAIT_L(0); PG8_BAR; PG8_MMA(0, 0, At, B0); PG8_MMA(0, 1, At, B1); PG8_BAR; PG8_SCHED;
	s_setprio 1
	v_mfma_f32_16x16x32_bf16 v[44:47], v[36:39], v[196:199], v[44:47]
	v_mfma_f32_16x16x32_bf16 v[44:47], v[152:155], v[200:203], v[44:47]
	v_mfma_f32_16x16x32_bf16 v[40:43], v[160:163], v[200:203], v[40:43]
	v_mfma_f32_16x16x32_bf16 v[40:43], v[156:159], v[196:199], v[40:43]
	v_mfma_f32_16x16x32_bf16 v[20:23], v[156:159], v[204:207], v[20:23]
	v_mfma_f32_16x16x32_bf16 v[20:23], v[160:163], v[208:211], v[20:23]
	v_mfma_f32_16x16x32_bf16 v[24:27], v[152:155], v[208:211], v[24:27]
	v_mfma_f32_16x16x32_bf16 v[24:27], v[36:39], v[204:207], v[24:27]
	s_setprio 0
	s_setprio 1
	v_mfma_f32_16x16x32_bf16 v[48:51], v[172:175], v[180:183], v[48:51]
	v_mfma_f32_16x16x32_bf16 v[32:35], v[164:167], v[188:191], v[32:35]
	v_mfma_f32_16x16x32_bf16 v[28:31], v[172:175], v[188:191], v[28:31]
	v_mfma_f32_16x16x32_bf16 v[16:19], v[164:167], v[196:199], v[16:19]
	v_mfma_f32_16x16x32_bf16 v[12:15], v[172:175], v[196:199], v[12:15]
	v_mfma_f32_16x16x32_bf16 v[8:11], v[164:167], v[204:207], v[8:11]
	v_mfma_f32_16x16x32_bf16 v[4:7], v[172:175], v[204:207], v[4:7]
	v_mfma_f32_16x16x32_bf16 v[36:39], v[164:167], v[180:183], v[52:55]
	v_mfma_f32_16x16x32_bf16 v[48:51], v[176:179], v[184:187], v[48:51]
	v_mfma_f32_16x16x32_bf16 v[32:35], v[168:171], v[192:195], v[32:35]
	v_mfma_f32_16x16x32_bf16 v[28:31], v[176:179], v[192:195], v[28:31]
	v_mfma_f32_16x16x32_bf16 v[16:19], v[168:171], v[200:203], v[16:19]
	v_mfma_f32_16x16x32_bf16 v[12:15], v[176:179], v[200:203], v[12:15]
	v_mfma_f32_16x16x32_bf16 v[8:11], v[168:171], v[208:211], v[8:11]
	v_mfma_f32_16x16x32_bf16 v[4:7], v[176:179], v[208:211], v[4:7]
	v_mfma_f32_16x16x32_bf16 v[36:39], v[168:171], v[184:187], v[36:39]
	s_setprio 0
	s_barrier
	s_add_i32 s68, 0, 0x18000
	v_add_u32_e32 v151, s68, v148
	s_add_i32 s69, 0, 0x1c000
	ds_read_b128 v[52:55], v151
	ds_read_b128 v[152:155], v151 offset:1024
	ds_read_b128 v[156:159], v151 offset:2048
	ds_read_b128 v[160:163], v151 offset:3072
	v_add_u32_e32 v151, s69, v148
	ds_read_b128 v[164:167], v151
	ds_read_b128 v[168:171], v151 offset:1024
	ds_read_b128 v[172:175], v151 offset:2048
	ds_read_b128 v[176:179], v151 offset:3072
	s_add_u32 s28, s28, 0x4000
	s_addc_u32 s29, s29, 0
	s_mov_b32 m0, s36
	ds_read_b128 v[180:183], v150 offset:32768
	ds_read_b128 v[184:187], v150 offset:33792
	ds_read_b128 v[188:191], v150 offset:34816
	ds_read_b128 v[192:195], v150 offset:35840
	ds_read_b128 v[196:199], v150 offset:36864
	ds_read_b128 v[200:203], v150 offset:37888
	ds_read_b128 v[204:207], v150 offset:38912
	ds_read_b128 v[208:211], v150 offset:39936
	global_load_lds_dwordx4 v136, s[28:29]
	s_mov_b32 m0, s37
	s_nop 0
	global_load_lds_dwordx4 v140, s[28:29]
	s_waitcnt vmcnt(8)
	s_waitcnt lgkmcnt(0)
	v_mfma_f32_16x16x32_bf16 v[132:135], v[52:55], v[180:183], v[132:135]
	v_mfma_f32_16x16x32_bf16 v[132:135], v[152:155], v[184:187], v[132:135]
	v_mfma_f32_16x16x32_bf16 v[128:131], v[160:163], v[184:187], v[128:131]
	v_mfma_f32_16x16x32_bf16 v[128:131], v[156:159], v[180:183], v[128:131]
	v_mfma_f32_16x16x32_bf16 v[120:123], v[156:159], v[188:191], v[120:123]
	v_mfma_f32_16x16x32_bf16 v[120:123], v[160:163], v[192:195], v[120:123]
	v_mfma_f32_16x16x32_bf16 v[124:127], v[152:155], v[192:195], v[124:127]
	v_mfma_f32_16x16x32_bf16 v[124:127], v[52:55], v[188:191], v[124:127]
	s_barrier
	s_setprio 1
	v_mfma_f32_16x16x32_bf16 v[108:111], v[52:55], v[196:199], v[108:111]
	v_mfma_f32_16x16x32_bf16 v[108:111], v[152:155], v[200:203], v[108:111]
	v_mfma_f32_16x16x32_bf16 v[104:107], v[160:163], v[200:203], v[104:107]
	v_mfma_f32_16x16x32_bf16 v[104:107], v[156:159], v[196:199], v[104:107]
	v_mfma_f32_16x16x32_bf16 v[88:91], v[156:159], v[204:207], v[88:91]
	v_mfma_f32_16x16x32_bf16 v[88:91], v[160:163], v[208:211], v[88:91]
	v_mfma_f32_16x16x32_bf16 v[92:95], v[152:155], v[208:211], v[92:95]
	v_mfma_f32_16x16x32_bf16 v[92:95], v[52:55], v[204:207], v[92:95]
	s_setprio 0
	s_setprio 1
	v_mfma_f32_16x16x32_bf16 v[76:79], v[164:167], v[204:207], v[76:79]
	v_mfma_f32_16x16x32_bf16 v[76:79], v[168:171], v[208:211], v[76:79]
	v_mfma_f32_16x16x32_bf16 v[116:119], v[168:171], v[184:187], v[116:119]
	v_mfma_f32_16x16x32_bf16 v[116:119], v[164:167], v[180:183], v[116:119]
	v_mfma_f32_16x16x32_bf16 v[112:115], v[172:175], v[180:183], v[112:115]
	v_mfma_f32_16x16x32_bf16 v[112:115], v[176:179], v[184:187], v[112:115]
	v_mfma_f32_16x16x32_bf16 v[96:99], v[176:179], v[192:195], v[96:99]
	v_mfma_f32_16x16x32_bf16 v[96:99], v[172:175], v[188:191], v[96:99]
	v_mfma_f32_16x16x32_bf16 v[100:103], v[164:167], v[188:191], v[100:103]
	v_mfma_f32_16x16x32_bf16 v[100:103], v[168:171], v[192:195], v[100:103]
	v_mfma_f32_16x16x32_bf16 v[84:87], v[168:171], v[200:203], v[84:87]
	v_mfma_f32_16x16x32_bf16 v[84:87], v[164:167], v[196:199], v[84:87]
	v_mfma_f32_16x16x32_bf16 v[80:83], v[172:175], v[196:199], v[80:83]
	v_mfma_f32_16x16x32_bf16 v[80:83], v[176:179], v[200:203], v[80:83]
	v_mfma_f32_16x16x32_bf16 v[72:75], v[176:179], v[208:211], v[72:75]
	v_mfma_f32_16x16x32_bf16 v[72:75], v[172:175], v[204:207], v[72:75]
	s_setprio 0
	s_barrier
; #define PG8_STAGE(bufoff, gbase, voff) do { _Pragma("unroll") for (int _i = 0; _i < 2; ++_i) \
;         __builtin_amdgcn_global_load_lds((const unsigned*)((const char*)(gbase) + (voff)[_i]), (PG8_LAS unsigned*)(lds + (bufoff) + ldsw + _i * 8192), 16, 0, 0); } while (0)
; #define PG8_LDA(dst, b, h) do { _Pragma("unroll") for (int m = 0; m < 4; ++m) _Pragma("unroll") for (int k = 0; k < 2; ++k) dst[m][k] = *(const PG8_LAS bf16x8*)(lds + PG8_SA(b, h) + aoff + m * 2048 + k * 1024); } while (0)
; #define PG8_MMA(ai, bj, At, Bt) do { __builtin_amdgcn_s_setprio(1); _Pragma("unroll") for (int m = 0; m < 4; ++m) _Pragma("unroll") for (int n = 0; n < 2; ++n) _Pragma("unroll") for (int k = 0; k < 2; ++k) \
;         acc[ai][bj][m][n] = __builtin_amdgcn_mfma_f32_16x16x32_bf16(Bt[n][k], At[m][k], acc[ai][bj][m][n], 0, 0, 0); __builtin_amdgcn_s_setprio(0); } while (0)
; #define PG8_WAIT_V(n) asm volatile("s_waitcnt vmcnt(" #n ")" ::: "memory")
; #define PG8_WAIT_L(n) asm volatile("s_waitcnt lgkmcnt(" #n ")" ::: "memory")
; #define PG8_BAR __builtin_amdgcn_s_barrier()
; #define PG8_SCHED __builtin_amdgcn_sched_barrier(0)
; template <class Epi, class Sched, bool ALIGN_EPI = false, bool SP2 = false, bool ABLK = false, bool BBLK = false>
; __device__ __forceinline__ void gemm_phase(PG8_LAS unsigned char* lds, const Gemm g, const Sched& S, const Epi& E) {
;     ...
;         for (int t = 0; t < nt; t += 2) {
;             const bool last = (t == nt - 2);
;     ...
;             PG8_LDA(At, 1, 1); PG8_STAGE(PG8_SB(1, 0), b3, voffB); PG8_STAGE(PG8_SB(1, 1), b3 + hstepB, voffB); PG8_STAGE(PG8_SA(1, 0), a3, voffA);
;             PG8_WAIT_V(8); PG8_WAIT_L(0); PG8_BAR; PG8_MMA(1, 0, At, B0); PG8_MMA(1, 1, At, B1); PG8_BAR; PG8_SCHED;
	s_add_u32 s28, s26, 0x8000
	s_addc_u32 s29, s27, 0
	s_add_i32 s68, s68, s34
	s_mov_b32 m0, s68
	ds_read_b128 v[180:183], v150 offset:49152
	ds_read_b128 v[184:187], v150 offset:50176
	ds_read_b128 v[188:191], v150 offset:51200
	ds_read_b128 v[192:195], v150 offset:52224
	ds_read_b128 v[196:199], v150 offset:53248
	ds_read_b128 v[200:203], v150 offset:54272
	ds_read_b128 v[204:207], v150 offset:55296
	ds_read_b128 v[208:211], v150 offset:56320
	global_load_lds_dwordx4 v138, s[28:29]
	s_add_i32 m0, s68, 0x2000
	s_add_u32 s26, s26, 0xc000
	s_addc_u32 s27, s27, 0
	global_load_lds_dwordx4 v142, s[28:29]
	s_add_i32 s28, s69, s34
	s_mov_b32 m0, s28
	s_nop 0
	global_load_lds_dwordx4 v138, s[26:27]
	s_add_i32 m0, s28, 0x2000
	s_nop 0
	global_load_lds_dwordx4 v142, s[26:27]
	s_mov_b32 m0, s64
	s_nop 0
	global_load_lds_dwordx4 v136, s[24:25]
	s_mov_b32 m0, s65
	s_nop 0
	global_load_lds_dwordx4 v140, s[24:25]
	s_waitcnt vmcnt(8)
	s_waitcnt lgkmcnt(0)
	v_mfma_f32_16x16x32_bf16 v[68:71], v[52:55], v[180:183], v[68:71]
	v_mfma_f32_16x16x32_bf16 v[68:71], v[152:155], v[184:187], v[68:71]
	v_mfma_f32_16x16x32_bf16 v[64:67], v[160:163], v[184:187], v[64:67]
	v_mfma_f32_16x16x32_bf16 v[64:67], v[156:159], v[180:183], v[64:67]
	v_mfma_f32_16x16x32_bf16 v[56:59], v[156:159], v[188:191], v[56:59]
	v_mfma_f32_16x16x32_bf16 v[56:59], v[160:163], v[192:195], v[56:59]
	v_mfma_f32_16x16x32_bf16 v[60:63], v[152:155], v[192:195], v[60:63]
	v_mfma_f32_16x16x32_bf16 v[60:63], v[52:55], v[188:191], v[60:63]
	s_barrier
	s_setprio 1
	v_mfma_f32_16x16x32_bf16 v[44:47], v[52:55], v[196:199], v[44:47]
	v_mfma_f32_16x16x32_bf16 v[44:47], v[152:155], v[200:203], v[44:47]
	v_mfma_f32_16x16x32_bf16 v[40:43], v[160:163], v[200:203], v[40:43]
	v_mfma_f32_16x16x32_bf16 v[40:43], v[156:159], v[196:199], v[40:43]
	v_mfma_f32_16x16x32_bf16 v[20:23], v[156:159], v[204:207], v[20:23]
	v_mfma_f32_16x16x32_bf16 v[20:23], v[160:163], v[208:211], v[20:23]
	v_mfma_f32_16x16x32_bf16 v[24:27], v[152:155], v[208:211], v[24:27]
	v_mfma_f32_16x16x32_bf16 v[24:27], v[52:55], v[204:207], v[24:27]
	s_setprio 0
	s_setprio 1
	v_mfma_f32_16x16x32_bf16 v[36:39], v[164:167], v[180:183], v[36:39]
	v_mfma_f32_16x16x32_bf16 v[52:55], v[168:171], v[184:187], v[36:39]
	v_mfma_f32_16x16x32_bf16 v[36:39], v[172:175], v[180:183], v[48:51]
	v_mfma_f32_16x16x32_bf16 v[32:35], v[164:167], v[188:191], v[32:35]
	v_mfma_f32_16x16x32_bf16 v[28:31], v[172:175], v[188:191], v[28:31]
	v_mfma_f32_16x16x32_bf16 v[16:19], v[164:167], v[196:199], v[16:19]
	v_mfma_f32_16x16x32_bf16 v[12:15], v[172:175], v[196:199], v[12:15]
	v_mfma_f32_16x16x32_bf16 v[8:11], v[164:167], v[204:207], v[8:11]
	v_mfma_f32_16x16x32_bf16 v[4:7], v[172:175], v[204:207], v[4:7]
	v_mfma_f32_16x16x32_bf16 v[48:51], v[176:179], v[184:187], v[36:39]
	v_mfma_f32_16x16x32_bf16 v[32:35], v[168:171], v[192:195], v[32:35]
	v_mfma_f32_16x16x32_bf16 v[28:31], v[176:179], v[192:195], v[28:31]
	v_mfma_f32_16x16x32_bf16 v[16:19], v[168:171], v[200:203], v[16:19]
	v_mfma_f32_16x16x32_bf16 v[12:15], v[176:179], v[200:203], v[12:15]
	v_mfma_f32_16x16x32_bf16 v[8:11], v[168:171], v[208:211], v[8:11]
	v_mfma_f32_16x16x32_bf16 v[4:7], v[176:179], v[208:211], v[4:7]
	s_setprio 0
	s_barrier
	s_add_i32 s13, s13, 2
	s_add_u32 s22, s22, 0x10000
	s_addc_u32 s23, s23, 0
	s_add_u32 s82, s82, 0x10000
	s_addc_u32 vcc_lo, vcc_lo, 0
	s_cmp_gt_u32 s13, 29
	s_cbranch_scc0 .LBB0_2111
	s_and_b64 vcc, exec, s[6:7]
	s_movk_i32 s77, 0x1000
	s_cbranch_vccz .LBB0_2114
	s_barrier
